# in-proj epilogue stores (PROJ and gate tiles) as sc1 write-through: less dirty L2 at the pre-attention grid barrier and less L2 pollution
# speedup vs baseline: 1.0144x; 1.0144x over previous
; __device__ __forceinline__ unsigned cvt_pk_bf16(float lo, float hi) { f32x2 v = {lo, hi}; bf16x2_t b = __builtin_convertvector(v, bf16x2_t); return __builtin_bit_cast(unsigned, b); }
; __device__ __forceinline__ float fast_exp2(float x) { return __builtin_amdgcn_exp2f(x); }
; __device__ __forceinline__ float fast_rcp(float x) { return __builtin_amdgcn_rcpf(x); }
;     __device__ __forceinline__ void operator()(ACC_T, const Unit& u, int wr, int wc, int fr, int fq) const {
;     ...
;             const int col0 = (u.pn - 14) * BM + cw;
;             f32x4 bv[2][2];
; #pragma unroll
;             for (int bj = 0; bj < 2; ++bj)
; #pragma unroll
;                 for (int n = 0; n < 2; ++n) bv[bj][n] = *(const f32x4*)(bias + col0 + bj * HALF + 4 * n);
; #pragma unroll
;             for (int ai = 0; ai < 2; ++ai)
; #pragma unroll
;                 for (int m = 0; m < 4; ++m) { bf16_t* rowp = Gt + (size_t)(row0 + ai * HALF + m * 16) * GW + col0;
; #pragma unroll
;                     for (int bj = 0; bj < 2; ++bj) { float r[8];
; #pragma unroll
;                         for (int n = 0; n < 2; ++n)
; #pragma unroll
;                             for (int e = 0; e < 4; ++e) { const float x = acc[ai][bj][m][n][e] + bv[bj][n][e]; r[n * 4 + e] = fast_rcp(1.f + fast_exp2(-x * LOG2E)); }
;                         u32x4 w; w.x = cvt_pk_bf16(r[0], r[1]); w.y = cvt_pk_bf16(r[2], r[3]); w.z = cvt_pk_bf16(r[4], r[5]); w.w = cvt_pk_bf16(r[6], r[7]);
;                         *(u32x4*)(rowp + bj * HALF) = w; } }
.LBB0_303:
	v_lshl_add_u32 v158, s2, 8, v176
	s_mov_b64 s[0:1], -1
	s_cmp_gt_i32 s40, 13
	v_or_b32_e32 v168, 16, v158
	v_or_b32_e32 v166, 32, v158
	v_or_b32_e32 v164, 48, v158
	v_add_u32_e32 v162, 0x80, v158
	v_add_u32_e32 v160, 0x90, v158
	s_cbranch_scc0 .LBB0_305
	v_lshl_add_u32 v0, s40, 8, v179
	v_lshl_add_u64 v[134:135], v[0:1], 2, s[10:11]
	global_load_dwordx4 v[138:141], v[134:135], off offset:16
	global_load_dwordx4 v[142:145], v[134:135], off
	global_load_dwordx4 v[130:133], v[134:135], off offset:528
	s_nop 0
	global_load_dwordx4 v[134:137], v[134:135], off offset:512
	v_lshlrev_b64 v[172:173], 1, v[0:1]
	v_readlane_b32 s0, v251, 58
	v_readlane_b32 s1, v251, 59
	s_movk_i32 s2, 0x1800
	s_waitcnt vmcnt(0)
	v_add_f32_e32 v165, v122, v138
	v_add_f32_e32 v0, v126, v142
	v_add_f32_e32 v159, v127, v143
	v_add_f32_e32 v161, v128, v144
	v_add_f32_e32 v163, v129, v145
	v_add_f32_e32 v167, v123, v139
	v_add_f32_e32 v169, v124, v140
	v_add_f32_e32 v181, v125, v141
	v_mul_f32_e32 v0, 0xbfb8aa3b, v0
	v_mul_f32_e32 v159, 0xbfb8aa3b, v159
	v_mul_f32_e32 v161, 0xbfb8aa3b, v161
	v_mul_f32_e32 v163, 0xbfb8aa3b, v163
	v_mul_f32_e32 v165, 0xbfb8aa3b, v165
	v_mul_f32_e32 v167, 0xbfb8aa3b, v167
	v_mul_f32_e32 v169, 0xbfb8aa3b, v169
	v_mul_f32_e32 v181, 0xbfb8aa3b, v181
	v_exp_f32_e32 v0, v0
	v_exp_f32_e32 v159, v159
	v_exp_f32_e32 v161, v161
	v_exp_f32_e32 v163, v163
	v_exp_f32_e32 v165, v165
	v_exp_f32_e32 v167, v167
	v_exp_f32_e32 v169, v169
	v_exp_f32_e32 v181, v181
	v_add_f32_e32 v0, 1.0, v0
	v_add_f32_e32 v159, 1.0, v159
	v_add_f32_e32 v161, 1.0, v161
	v_add_f32_e32 v163, 1.0, v163
	v_add_f32_e32 v165, 1.0, v165
	v_add_f32_e32 v167, 1.0, v167
	v_add_f32_e32 v169, 1.0, v169
	v_add_f32_e32 v181, 1.0, v181
	v_rcp_f32_e32 v0, v0
	v_rcp_f32_e32 v159, v159
	v_rcp_f32_e32 v161, v161
	v_rcp_f32_e32 v163, v163
	v_rcp_f32_e32 v165, v165
	v_rcp_f32_e32 v167, v167
	v_rcp_f32_e32 v169, v169
	v_rcp_f32_e32 v181, v181
	v_cvt_pk_bf16_f32 v182, v0, v159
	v_cvt_pk_bf16_f32 v183, v161, v163
	v_cvt_pk_bf16_f32 v184, v165, v167
	v_cvt_pk_bf16_f32 v185, v169, v181
	v_add_f32_e32 v0, v118, v134
	v_add_f32_e32 v159, v119, v135
	v_add_f32_e32 v161, v120, v136
	v_add_f32_e32 v163, v121, v137
	v_add_f32_e32 v165, v114, v130
	v_add_f32_e32 v167, v115, v131
	v_add_f32_e32 v169, v116, v132
	v_add_f32_e32 v181, v117, v133
	v_mul_f32_e32 v0, 0xbfb8aa3b, v0
	v_mul_f32_e32 v159, 0xbfb8aa3b, v159
	v_mul_f32_e32 v161, 0xbfb8aa3b, v161
	v_mul_f32_e32 v163, 0xbfb8aa3b, v163
	v_mul_f32_e32 v165, 0xbfb8aa3b, v165
	v_mul_f32_e32 v167, 0xbfb8aa3b, v167
	v_mul_f32_e32 v169, 0xbfb8aa3b, v169
	v_mul_f32_e32 v181, 0xbfb8aa3b, v181
	v_exp_f32_e32 v0, v0
	v_exp_f32_e32 v159, v159
	v_exp_f32_e32 v161, v161
	v_exp_f32_e32 v163, v163
	v_exp_f32_e32 v165, v165
	v_exp_f32_e32 v167, v167
	v_exp_f32_e32 v169, v169
	v_exp_f32_e32 v181, v181
	v_add_f32_e32 v0, 1.0, v0
	v_add_f32_e32 v159, 1.0, v159
	v_add_f32_e32 v161, 1.0, v161
	v_add_f32_e32 v163, 1.0, v163
	v_add_f32_e32 v165, 1.0, v165
	v_add_f32_e32 v167, 1.0, v167
	v_add_f32_e32 v169, 1.0, v169
	v_add_f32_e32 v181, 1.0, v181
	v_rcp_f32_e32 v0, v0
	v_rcp_f32_e32 v159, v159
	v_rcp_f32_e32 v161, v161
	v_rcp_f32_e32 v163, v163
	v_rcp_f32_e32 v165, v165
	v_rcp_f32_e32 v167, v167
	v_rcp_f32_e32 v169, v169
	v_rcp_f32_e32 v181, v181
	v_mov_b64_e32 v[170:171], s[0:1]
	v_mad_i64_i32 v[174:175], s[0:1], v158, s2, v[170:171]
	v_lshl_add_u64 v[174:175], v[174:175], 0, v[172:173]
	global_store_dwordx4 v[174:175], v[182:185], off sc1
	s_nop 1
	v_cvt_pk_bf16_f32 v182, v0, v159
	v_cvt_pk_bf16_f32 v183, v161, v163
	v_cvt_pk_bf16_f32 v184, v165, v167
	v_cvt_pk_bf16_f32 v185, v169, v181
	v_add_f32_e32 v0, v110, v142
	v_add_f32_e32 v159, v111, v143
	v_add_f32_e32 v161, v112, v144
	v_add_f32_e32 v163, v113, v145
	v_add_f32_e32 v165, v106, v138
	v_add_f32_e32 v167, v107, v139
	v_add_f32_e32 v169, v108, v140
	v_add_f32_e32 v181, v109, v141
	v_mul_f32_e32 v0, 0xbfb8aa3b, v0
	v_mul_f32_e32 v159, 0xbfb8aa3b, v159
	v_mul_f32_e32 v161, 0xbfb8aa3b, v161
	v_mul_f32_e32 v163, 0xbfb8aa3b, v163
	v_mul_f32_e32 v165, 0xbfb8aa3b, v165
	v_mul_f32_e32 v167, 0xbfb8aa3b, v167
	v_mul_f32_e32 v169, 0xbfb8aa3b, v169
	v_mul_f32_e32 v181, 0xbfb8aa3b, v181
	v_exp_f32_e32 v0, v0
	v_exp_f32_e32 v159, v159
	v_exp_f32_e32 v161, v161
	v_exp_f32_e32 v163, v163
	v_exp_f32_e32 v165, v165
	v_exp_f32_e32 v167, v167
	v_exp_f32_e32 v169, v169
	v_exp_f32_e32 v181, v181
	v_add_f32_e32 v0, 1.0, v0
	v_add_f32_e32 v159, 1.0, v159
	v_add_f32_e32 v161, 1.0, v161
	v_add_f32_e32 v163, 1.0, v163
	v_add_f32_e32 v165, 1.0, v165
	v_add_f32_e32 v167, 1.0, v167
	v_add_f32_e32 v169, 1.0, v169
	v_add_f32_e32 v181, 1.0, v181
	v_rcp_f32_e32 v0, v0
	v_rcp_f32_e32 v159, v159
	v_rcp_f32_e32 v161, v161
	v_rcp_f32_e32 v163, v163
	v_rcp_f32_e32 v165, v165
	v_rcp_f32_e32 v167, v167
	v_rcp_f32_e32 v169, v169
	v_rcp_f32_e32 v181, v181
	global_store_dwordx4 v[174:175], v[182:185], off offset:256 sc1
	v_mad_i64_i32 v[174:175], s[0:1], v168, s2, v[170:171]
	s_nop 0
	v_cvt_pk_bf16_f32 v182, v0, v159
	v_cvt_pk_bf16_f32 v183, v161, v163
	v_cvt_pk_bf16_f32 v184, v165, v167
	v_cvt_pk_bf16_f32 v185, v169, v181
	v_add_f32_e32 v0, v102, v134
	v_add_f32_e32 v159, v103, v135
	v_add_f32_e32 v161, v104, v136
	v_add_f32_e32 v163, v105, v137
	v_add_f32_e32 v165, v98, v130
	v_add_f32_e32 v167, v99, v131
	v_add_f32_e32 v169, v100, v132
	v_add_f32_e32 v181, v101, v133
	v_mul_f32_e32 v0, 0xbfb8aa3b, v0
	v_mul_f32_e32 v159, 0xbfb8aa3b, v159
	v_mul_f32_e32 v161, 0xbfb8aa3b, v161
	v_mul_f32_e32 v163, 0xbfb8aa3b, v163
	v_mul_f32_e32 v165, 0xbfb8aa3b, v165
	v_mul_f32_e32 v167, 0xbfb8aa3b, v167
	v_mul_f32_e32 v169, 0xbfb8aa3b, v169
	v_mul_f32_e32 v181, 0xbfb8aa3b, v181
; __device__ __forceinline__ unsigned cvt_pk_bf16(float lo, float hi) { f32x2 v = {lo, hi}; bf16x2_t b = __builtin_convertvector(v, bf16x2_t); return __builtin_bit_cast(unsigned, b); }
; __device__ __forceinline__ float fast_exp2(float x) { return __builtin_amdgcn_exp2f(x); }
; __device__ __forceinline__ float fast_rcp(float x) { return __builtin_amdgcn_rcpf(x); }
;     __device__ __forceinline__ void operator()(ACC_T, const Unit& u, int wr, int wc, int fr, int fq) const {
;     ...
;             for (int ai = 0; ai < 2; ++ai)
; #pragma unroll
;                 for (int m = 0; m < 4; ++m) { bf16_t* rowp = Gt + (size_t)(row0 + ai * HALF + m * 16) * GW + col0;
; #pragma unroll
;                     for (int bj = 0; bj < 2; ++bj) { float r[8];
; #pragma unroll
;                         for (int n = 0; n < 2; ++n)
; #pragma unroll
;                             for (int e = 0; e < 4; ++e) { const float x = acc[ai][bj][m][n][e] + bv[bj][n][e]; r[n * 4 + e] = fast_rcp(1.f + fast_exp2(-x * LOG2E)); }
;                         u32x4 w; w.x = cvt_pk_bf16(r[0], r[1]); w.y = cvt_pk_bf16(r[2], r[3]); w.z = cvt_pk_bf16(r[4], r[5]); w.w = cvt_pk_bf16(r[6], r[7]);
;                         *(u32x4*)(rowp + bj * HALF) = w; } }
	v_exp_f32_e32 v0, v0
	v_exp_f32_e32 v159, v159
	v_exp_f32_e32 v161, v161
	v_exp_f32_e32 v163, v163
	v_exp_f32_e32 v165, v165
	v_exp_f32_e32 v167, v167
	v_exp_f32_e32 v169, v169
	v_exp_f32_e32 v181, v181
	v_add_f32_e32 v0, 1.0, v0
	v_add_f32_e32 v159, 1.0, v159
	v_add_f32_e32 v161, 1.0, v161
	v_add_f32_e32 v163, 1.0, v163
	v_add_f32_e32 v165, 1.0, v165
	v_add_f32_e32 v167, 1.0, v167
	v_add_f32_e32 v169, 1.0, v169
	v_add_f32_e32 v181, 1.0, v181
	v_rcp_f32_e32 v0, v0
	v_rcp_f32_e32 v159, v159
	v_rcp_f32_e32 v161, v161
	v_rcp_f32_e32 v163, v163
	v_rcp_f32_e32 v165, v165
	v_rcp_f32_e32 v167, v167
	v_rcp_f32_e32 v169, v169
	v_rcp_f32_e32 v181, v181
	v_lshl_add_u64 v[174:175], v[174:175], 0, v[172:173]
	global_store_dwordx4 v[174:175], v[182:185], off sc1
	s_nop 1
	v_cvt_pk_bf16_f32 v182, v0, v159
	v_cvt_pk_bf16_f32 v183, v161, v163
	v_cvt_pk_bf16_f32 v184, v165, v167
	v_cvt_pk_bf16_f32 v185, v169, v181
	v_add_f32_e32 v0, v94, v142
	v_add_f32_e32 v159, v95, v143
	v_add_f32_e32 v161, v96, v144
	v_add_f32_e32 v163, v97, v145
	v_add_f32_e32 v165, v90, v138
	v_add_f32_e32 v167, v91, v139
	v_add_f32_e32 v169, v92, v140
	v_add_f32_e32 v181, v93, v141
	v_mul_f32_e32 v0, 0xbfb8aa3b, v0
	v_mul_f32_e32 v159, 0xbfb8aa3b, v159
	v_mul_f32_e32 v161, 0xbfb8aa3b, v161
	v_mul_f32_e32 v163, 0xbfb8aa3b, v163
	v_mul_f32_e32 v165, 0xbfb8aa3b, v165
	v_mul_f32_e32 v167, 0xbfb8aa3b, v167
	v_mul_f32_e32 v169, 0xbfb8aa3b, v169
	v_mul_f32_e32 v181, 0xbfb8aa3b, v181
	v_exp_f32_e32 v0, v0
	v_exp_f32_e32 v159, v159
	v_exp_f32_e32 v161, v161
	v_exp_f32_e32 v163, v163
	v_exp_f32_e32 v165, v165
	v_exp_f32_e32 v167, v167
	v_exp_f32_e32 v169, v169
	v_exp_f32_e32 v181, v181
	v_add_f32_e32 v0, 1.0, v0
	v_add_f32_e32 v159, 1.0, v159
	v_add_f32_e32 v161, 1.0, v161
	v_add_f32_e32 v163, 1.0, v163
	v_add_f32_e32 v165, 1.0, v165
	v_add_f32_e32 v167, 1.0, v167
	v_add_f32_e32 v169, 1.0, v169
	v_add_f32_e32 v181, 1.0, v181
	v_rcp_f32_e32 v0, v0
	v_rcp_f32_e32 v159, v159
	v_rcp_f32_e32 v161, v161
	v_rcp_f32_e32 v163, v163
	v_rcp_f32_e32 v165, v165
	v_rcp_f32_e32 v167, v167
	v_rcp_f32_e32 v169, v169
	v_rcp_f32_e32 v181, v181
	global_store_dwordx4 v[174:175], v[182:185], off offset:256 sc1
	v_mad_i64_i32 v[174:175], s[0:1], v166, s2, v[170:171]
	s_nop 0
	v_cvt_pk_bf16_f32 v182, v0, v159
	v_cvt_pk_bf16_f32 v183, v161, v163
	v_cvt_pk_bf16_f32 v184, v165, v167
	v_cvt_pk_bf16_f32 v185, v169, v181
	v_add_f32_e32 v0, v86, v134
	v_add_f32_e32 v159, v87, v135
	v_add_f32_e32 v161, v88, v136
	v_add_f32_e32 v163, v89, v137
	v_add_f32_e32 v165, v82, v130
	v_add_f32_e32 v167, v83, v131
	v_add_f32_e32 v169, v84, v132
	v_add_f32_e32 v181, v85, v133
	v_mul_f32_e32 v0, 0xbfb8aa3b, v0
	v_mul_f32_e32 v159, 0xbfb8aa3b, v159
	v_mul_f32_e32 v161, 0xbfb8aa3b, v161
	v_mul_f32_e32 v163, 0xbfb8aa3b, v163
	v_mul_f32_e32 v165, 0xbfb8aa3b, v165
	v_mul_f32_e32 v167, 0xbfb8aa3b, v167
	v_mul_f32_e32 v169, 0xbfb8aa3b, v169
	v_mul_f32_e32 v181, 0xbfb8aa3b, v181
	v_exp_f32_e32 v0, v0
	v_exp_f32_e32 v159, v159
	v_exp_f32_e32 v161, v161
	v_exp_f32_e32 v163, v163
	v_exp_f32_e32 v165, v165
	v_exp_f32_e32 v167, v167
	v_exp_f32_e32 v169, v169
	v_exp_f32_e32 v181, v181
	v_add_f32_e32 v0, 1.0, v0
	v_add_f32_e32 v159, 1.0, v159
	v_add_f32_e32 v161, 1.0, v161
	v_add_f32_e32 v163, 1.0, v163
	v_add_f32_e32 v165, 1.0, v165
	v_add_f32_e32 v167, 1.0, v167
	v_add_f32_e32 v169, 1.0, v169
	v_add_f32_e32 v181, 1.0, v181
	v_rcp_f32_e32 v0, v0
	v_rcp_f32_e32 v159, v159
	v_rcp_f32_e32 v161, v161
	v_rcp_f32_e32 v163, v163
	v_rcp_f32_e32 v165, v165
	v_rcp_f32_e32 v167, v167
	v_rcp_f32_e32 v169, v169
	v_rcp_f32_e32 v181, v181
	v_lshl_add_u64 v[174:175], v[174:175], 0, v[172:173]
	global_store_dwordx4 v[174:175], v[182:185], off sc1
	s_nop 1
	v_cvt_pk_bf16_f32 v182, v0, v159
	v_cvt_pk_bf16_f32 v183, v161, v163
	v_cvt_pk_bf16_f32 v184, v165, v167
	v_cvt_pk_bf16_f32 v185, v169, v181
	v_add_f32_e32 v0, v78, v142
	v_add_f32_e32 v159, v79, v143
	v_add_f32_e32 v161, v80, v144
	v_add_f32_e32 v163, v81, v145
	v_add_f32_e32 v165, v74, v138
	v_add_f32_e32 v167, v75, v139
	v_add_f32_e32 v169, v76, v140
	v_add_f32_e32 v181, v77, v141
	v_mul_f32_e32 v0, 0xbfb8aa3b, v0
	v_mul_f32_e32 v159, 0xbfb8aa3b, v159
	v_mul_f32_e32 v161, 0xbfb8aa3b, v161
	v_mul_f32_e32 v163, 0xbfb8aa3b, v163
	v_mul_f32_e32 v165, 0xbfb8aa3b, v165
	v_mul_f32_e32 v167, 0xbfb8aa3b, v167
	v_mul_f32_e32 v169, 0xbfb8aa3b, v169
	v_mul_f32_e32 v181, 0xbfb8aa3b, v181
	v_exp_f32_e32 v0, v0
	v_exp_f32_e32 v159, v159
	v_exp_f32_e32 v161, v161
	v_exp_f32_e32 v163, v163
	v_exp_f32_e32 v165, v165
	v_exp_f32_e32 v167, v167
	v_exp_f32_e32 v169, v169
	v_exp_f32_e32 v181, v181
	v_add_f32_e32 v0, 1.0, v0
	v_add_f32_e32 v159, 1.0, v159
	v_add_f32_e32 v161, 1.0, v161
	v_add_f32_e32 v163, 1.0, v163
	v_add_f32_e32 v165, 1.0, v165
	v_add_f32_e32 v167, 1.0, v167
	v_add_f32_e32 v169, 1.0, v169
	v_add_f32_e32 v181, 1.0, v181
	v_rcp_f32_e32 v0, v0
	v_rcp_f32_e32 v159, v159
	v_rcp_f32_e32 v161, v161
	v_rcp_f32_e32 v163, v163
	v_rcp_f32_e32 v165, v165
	v_rcp_f32_e32 v167, v167
	v_rcp_f32_e32 v169, v169
	v_rcp_f32_e32 v181, v181
	global_store_dwordx4 v[174:175], v[182:185], off offset:256 sc1
	v_mad_i64_i32 v[174:175], s[0:1], v164, s2, v[170:171]
	s_nop 0
	v_cvt_pk_bf16_f32 v182, v0, v159
	v_cvt_pk_bf16_f32 v183, v161, v163
	v_cvt_pk_bf16_f32 v184, v165, v167
	v_cvt_pk_bf16_f32 v185, v169, v181
	v_add_f32_e32 v0, v70, v134
	v_add_f32_e32 v159, v71, v135
	v_add_f32_e32 v161, v72, v136
	v_add_f32_e32 v163, v73, v137
	v_add_f32_e32 v165, v66, v130
	v_add_f32_e32 v167, v67, v131
	v_add_f32_e32 v169, v68, v132
	v_add_f32_e32 v181, v69, v133
	v_mul_f32_e32 v0, 0xbfb8aa3b, v0
	v_mul_f32_e32 v159, 0xbfb8aa3b, v159
; __device__ __forceinline__ unsigned cvt_pk_bf16(float lo, float hi) { f32x2 v = {lo, hi}; bf16x2_t b = __builtin_convertvector(v, bf16x2_t); return __builtin_bit_cast(unsigned, b); }
; __device__ __forceinline__ float fast_exp2(float x) { return __builtin_amdgcn_exp2f(x); }
; __device__ __forceinline__ float fast_rcp(float x) { return __builtin_amdgcn_rcpf(x); }
;     __device__ __forceinline__ void operator()(ACC_T, const Unit& u, int wr, int wc, int fr, int fq) const {
;     ...
;             for (int ai = 0; ai < 2; ++ai)
; #pragma unroll
;                 for (int m = 0; m < 4; ++m) { bf16_t* rowp = Gt + (size_t)(row0 + ai * HALF + m * 16) * GW + col0;
; #pragma unroll
;                     for (int bj = 0; bj < 2; ++bj) { float r[8];
; #pragma unroll
;                         for (int n = 0; n < 2; ++n)
; #pragma unroll
;                             for (int e = 0; e < 4; ++e) { const float x = acc[ai][bj][m][n][e] + bv[bj][n][e]; r[n * 4 + e] = fast_rcp(1.f + fast_exp2(-x * LOG2E)); }
;                         u32x4 w; w.x = cvt_pk_bf16(r[0], r[1]); w.y = cvt_pk_bf16(r[2], r[3]); w.z = cvt_pk_bf16(r[4], r[5]); w.w = cvt_pk_bf16(r[6], r[7]);
;                         *(u32x4*)(rowp + bj * HALF) = w; } }
	v_mul_f32_e32 v161, 0xbfb8aa3b, v161
	v_mul_f32_e32 v163, 0xbfb8aa3b, v163
	v_mul_f32_e32 v165, 0xbfb8aa3b, v165
	v_mul_f32_e32 v167, 0xbfb8aa3b, v167
	v_mul_f32_e32 v169, 0xbfb8aa3b, v169
	v_mul_f32_e32 v181, 0xbfb8aa3b, v181
	v_exp_f32_e32 v0, v0
	v_exp_f32_e32 v159, v159
	v_exp_f32_e32 v161, v161
	v_exp_f32_e32 v163, v163
	v_exp_f32_e32 v165, v165
	v_exp_f32_e32 v167, v167
	v_exp_f32_e32 v169, v169
	v_exp_f32_e32 v181, v181
	v_add_f32_e32 v0, 1.0, v0
	v_add_f32_e32 v159, 1.0, v159
	v_add_f32_e32 v161, 1.0, v161
	v_add_f32_e32 v163, 1.0, v163
	v_add_f32_e32 v165, 1.0, v165
	v_add_f32_e32 v167, 1.0, v167
	v_add_f32_e32 v169, 1.0, v169
	v_add_f32_e32 v181, 1.0, v181
	v_rcp_f32_e32 v0, v0
	v_rcp_f32_e32 v159, v159
	v_rcp_f32_e32 v161, v161
	v_rcp_f32_e32 v163, v163
	v_rcp_f32_e32 v165, v165
	v_rcp_f32_e32 v167, v167
	v_rcp_f32_e32 v169, v169
	v_rcp_f32_e32 v181, v181
	v_lshl_add_u64 v[174:175], v[174:175], 0, v[172:173]
	global_store_dwordx4 v[174:175], v[182:185], off sc1
	s_nop 1
	v_cvt_pk_bf16_f32 v182, v0, v159
	v_cvt_pk_bf16_f32 v183, v161, v163
	v_cvt_pk_bf16_f32 v184, v165, v167
	v_cvt_pk_bf16_f32 v185, v169, v181
	v_add_f32_e32 v0, v62, v142
	v_add_f32_e32 v159, v63, v143
	v_add_f32_e32 v161, v64, v144
	v_add_f32_e32 v163, v65, v145
	v_add_f32_e32 v165, v58, v138
	v_add_f32_e32 v167, v59, v139
	v_add_f32_e32 v169, v60, v140
	v_add_f32_e32 v181, v61, v141
	v_mul_f32_e32 v0, 0xbfb8aa3b, v0
	v_mul_f32_e32 v159, 0xbfb8aa3b, v159
	v_mul_f32_e32 v161, 0xbfb8aa3b, v161
	v_mul_f32_e32 v163, 0xbfb8aa3b, v163
	v_mul_f32_e32 v165, 0xbfb8aa3b, v165
	v_mul_f32_e32 v167, 0xbfb8aa3b, v167
	v_mul_f32_e32 v169, 0xbfb8aa3b, v169
	v_mul_f32_e32 v181, 0xbfb8aa3b, v181
	v_exp_f32_e32 v0, v0
	v_exp_f32_e32 v159, v159
	v_exp_f32_e32 v161, v161
	v_exp_f32_e32 v163, v163
	v_exp_f32_e32 v165, v165
	v_exp_f32_e32 v167, v167
	v_exp_f32_e32 v169, v169
	v_exp_f32_e32 v181, v181
	v_add_f32_e32 v0, 1.0, v0
	v_add_f32_e32 v159, 1.0, v159
	v_add_f32_e32 v161, 1.0, v161
	v_add_f32_e32 v163, 1.0, v163
	v_add_f32_e32 v165, 1.0, v165
	v_add_f32_e32 v167, 1.0, v167
	v_add_f32_e32 v169, 1.0, v169
	v_add_f32_e32 v181, 1.0, v181
	v_rcp_f32_e32 v0, v0
	v_rcp_f32_e32 v159, v159
	v_rcp_f32_e32 v161, v161
	v_rcp_f32_e32 v163, v163
	v_rcp_f32_e32 v165, v165
	v_rcp_f32_e32 v167, v167
	v_rcp_f32_e32 v169, v169
	v_rcp_f32_e32 v181, v181
	global_store_dwordx4 v[174:175], v[182:185], off offset:256 sc1
	v_mad_i64_i32 v[174:175], s[0:1], v162, s2, v[170:171]
	s_nop 0
	v_cvt_pk_bf16_f32 v182, v0, v159
	v_cvt_pk_bf16_f32 v183, v161, v163
	v_cvt_pk_bf16_f32 v184, v165, v167
	v_cvt_pk_bf16_f32 v185, v169, v181
	v_add_f32_e32 v0, v54, v134
	v_add_f32_e32 v159, v55, v135
	v_add_f32_e32 v161, v56, v136
	v_add_f32_e32 v163, v57, v137
	v_add_f32_e32 v165, v50, v130
	v_add_f32_e32 v167, v51, v131
	v_add_f32_e32 v169, v52, v132
	v_add_f32_e32 v181, v53, v133
	v_mul_f32_e32 v0, 0xbfb8aa3b, v0
	v_mul_f32_e32 v159, 0xbfb8aa3b, v159
	v_mul_f32_e32 v161, 0xbfb8aa3b, v161
	v_mul_f32_e32 v163, 0xbfb8aa3b, v163
	v_mul_f32_e32 v165, 0xbfb8aa3b, v165
	v_mul_f32_e32 v167, 0xbfb8aa3b, v167
	v_mul_f32_e32 v169, 0xbfb8aa3b, v169
	v_mul_f32_e32 v181, 0xbfb8aa3b, v181
	v_exp_f32_e32 v0, v0
	v_exp_f32_e32 v159, v159
	v_exp_f32_e32 v161, v161
	v_exp_f32_e32 v163, v163
	v_exp_f32_e32 v165, v165
	v_exp_f32_e32 v167, v167
	v_exp_f32_e32 v169, v169
	v_exp_f32_e32 v181, v181
	v_add_f32_e32 v0, 1.0, v0
	v_add_f32_e32 v159, 1.0, v159
	v_add_f32_e32 v161, 1.0, v161
	v_add_f32_e32 v163, 1.0, v163
	v_add_f32_e32 v165, 1.0, v165
	v_add_f32_e32 v167, 1.0, v167
	v_add_f32_e32 v169, 1.0, v169
	v_add_f32_e32 v181, 1.0, v181
	v_rcp_f32_e32 v0, v0
	v_rcp_f32_e32 v159, v159
	v_rcp_f32_e32 v161, v161
	v_rcp_f32_e32 v163, v163
	v_rcp_f32_e32 v165, v165
	v_rcp_f32_e32 v167, v167
	v_rcp_f32_e32 v169, v169
	v_rcp_f32_e32 v181, v181
	v_lshl_add_u64 v[174:175], v[174:175], 0, v[172:173]
	global_store_dwordx4 v[174:175], v[182:185], off sc1
	s_nop 1
	v_cvt_pk_bf16_f32 v182, v0, v159
	v_cvt_pk_bf16_f32 v183, v161, v163
	v_cvt_pk_bf16_f32 v184, v165, v167
	v_cvt_pk_bf16_f32 v185, v169, v181
	v_add_f32_e32 v0, v46, v142
	v_add_f32_e32 v159, v47, v143
	v_add_f32_e32 v161, v48, v144
	v_add_f32_e32 v163, v49, v145
	v_add_f32_e32 v165, v42, v138
	v_add_f32_e32 v167, v43, v139
	v_add_f32_e32 v169, v44, v140
	v_add_f32_e32 v181, v45, v141
	v_mul_f32_e32 v0, 0xbfb8aa3b, v0
	v_mul_f32_e32 v159, 0xbfb8aa3b, v159
	v_mul_f32_e32 v161, 0xbfb8aa3b, v161
	v_mul_f32_e32 v163, 0xbfb8aa3b, v163
	v_mul_f32_e32 v165, 0xbfb8aa3b, v165
	v_mul_f32_e32 v167, 0xbfb8aa3b, v167
	v_mul_f32_e32 v169, 0xbfb8aa3b, v169
	v_mul_f32_e32 v181, 0xbfb8aa3b, v181
	v_exp_f32_e32 v0, v0
	v_exp_f32_e32 v159, v159
	v_exp_f32_e32 v161, v161
	v_exp_f32_e32 v163, v163
	v_exp_f32_e32 v165, v165
	v_exp_f32_e32 v167, v167
	v_exp_f32_e32 v169, v169
	v_exp_f32_e32 v181, v181
	v_add_f32_e32 v0, 1.0, v0
	v_add_f32_e32 v159, 1.0, v159
	v_add_f32_e32 v161, 1.0, v161
	v_add_f32_e32 v163, 1.0, v163
	v_add_f32_e32 v165, 1.0, v165
	v_add_f32_e32 v167, 1.0, v167
	v_add_f32_e32 v169, 1.0, v169
	v_add_f32_e32 v181, 1.0, v181
	v_rcp_f32_e32 v0, v0
	v_rcp_f32_e32 v159, v159
	v_rcp_f32_e32 v161, v161
	v_rcp_f32_e32 v163, v163
	v_rcp_f32_e32 v165, v165
	v_rcp_f32_e32 v167, v167
	v_rcp_f32_e32 v169, v169
	v_rcp_f32_e32 v181, v181
	global_store_dwordx4 v[174:175], v[182:185], off offset:256 sc1
	v_mad_i64_i32 v[174:175], s[0:1], v160, s2, v[170:171]
	s_nop 0
	v_cvt_pk_bf16_f32 v182, v0, v159
	v_cvt_pk_bf16_f32 v183, v161, v163
	v_cvt_pk_bf16_f32 v184, v165, v167
	v_cvt_pk_bf16_f32 v185, v169, v181
	v_add_f32_e32 v0, v38, v134
	v_add_f32_e32 v159, v39, v135
	v_add_f32_e32 v161, v40, v136
; __device__ __forceinline__ unsigned cvt_pk_bf16(float lo, float hi) { f32x2 v = {lo, hi}; bf16x2_t b = __builtin_convertvector(v, bf16x2_t); return __builtin_bit_cast(unsigned, b); }
; __device__ __forceinline__ float fast_exp2(float x) { return __builtin_amdgcn_exp2f(x); }
; __device__ __forceinline__ float fast_rcp(float x) { return __builtin_amdgcn_rcpf(x); }
;     __device__ __forceinline__ void operator()(ACC_T, const Unit& u, int wr, int wc, int fr, int fq) const {
;     ...
;             for (int ai = 0; ai < 2; ++ai)
; #pragma unroll
;                 for (int m = 0; m < 4; ++m) { bf16_t* rowp = Gt + (size_t)(row0 + ai * HALF + m * 16) * GW + col0;
; #pragma unroll
;                     for (int bj = 0; bj < 2; ++bj) { float r[8];
; #pragma unroll
;                         for (int n = 0; n < 2; ++n)
; #pragma unroll
;                             for (int e = 0; e < 4; ++e) { const float x = acc[ai][bj][m][n][e] + bv[bj][n][e]; r[n * 4 + e] = fast_rcp(1.f + fast_exp2(-x * LOG2E)); }
;                         u32x4 w; w.x = cvt_pk_bf16(r[0], r[1]); w.y = cvt_pk_bf16(r[2], r[3]); w.z = cvt_pk_bf16(r[4], r[5]); w.w = cvt_pk_bf16(r[6], r[7]);
;                         *(u32x4*)(rowp + bj * HALF) = w; } }
	v_add_f32_e32 v163, v41, v137
	v_add_f32_e32 v165, v34, v130
	v_add_f32_e32 v167, v35, v131
	v_add_f32_e32 v169, v36, v132
	v_add_f32_e32 v181, v37, v133
	v_mul_f32_e32 v0, 0xbfb8aa3b, v0
	v_mul_f32_e32 v159, 0xbfb8aa3b, v159
	v_mul_f32_e32 v161, 0xbfb8aa3b, v161
	v_mul_f32_e32 v163, 0xbfb8aa3b, v163
	v_mul_f32_e32 v165, 0xbfb8aa3b, v165
	v_mul_f32_e32 v167, 0xbfb8aa3b, v167
	v_mul_f32_e32 v169, 0xbfb8aa3b, v169
	v_mul_f32_e32 v181, 0xbfb8aa3b, v181
	v_exp_f32_e32 v0, v0
	v_exp_f32_e32 v159, v159
	v_exp_f32_e32 v161, v161
	v_exp_f32_e32 v163, v163
	v_exp_f32_e32 v165, v165
	v_exp_f32_e32 v167, v167
	v_exp_f32_e32 v169, v169
	v_exp_f32_e32 v181, v181
	v_add_f32_e32 v0, 1.0, v0
	v_add_f32_e32 v159, 1.0, v159
	v_add_f32_e32 v161, 1.0, v161
	v_add_f32_e32 v163, 1.0, v163
	v_add_f32_e32 v165, 1.0, v165
	v_add_f32_e32 v167, 1.0, v167
	v_add_f32_e32 v169, 1.0, v169
	v_add_f32_e32 v181, 1.0, v181
	v_rcp_f32_e32 v0, v0
	v_rcp_f32_e32 v159, v159
	v_rcp_f32_e32 v161, v161
	v_rcp_f32_e32 v163, v163
	v_rcp_f32_e32 v165, v165
	v_rcp_f32_e32 v167, v167
	v_rcp_f32_e32 v169, v169
	v_rcp_f32_e32 v181, v181
	v_lshl_add_u64 v[174:175], v[174:175], 0, v[172:173]
	global_store_dwordx4 v[174:175], v[182:185], off sc1
	s_nop 1
	v_cvt_pk_bf16_f32 v182, v0, v159
	v_cvt_pk_bf16_f32 v183, v161, v163
	v_cvt_pk_bf16_f32 v184, v165, v167
	v_cvt_pk_bf16_f32 v185, v169, v181
	v_add_u32_e32 v0, 0xa0, v158
	global_store_dwordx4 v[174:175], v[182:185], off offset:256 sc1
	v_mad_i64_i32 v[174:175], s[0:1], v0, s2, v[170:171]
	v_add_f32_e32 v0, v30, v142
	v_add_f32_e32 v159, v31, v143
	v_mul_f32_e32 v0, 0xbfb8aa3b, v0
	v_mul_f32_e32 v159, 0xbfb8aa3b, v159
	v_exp_f32_e32 v0, v0
	v_exp_f32_e32 v159, v159
	v_add_f32_e32 v161, v32, v144
	v_add_f32_e32 v163, v33, v145
	v_add_f32_e32 v0, 1.0, v0
	v_add_f32_e32 v159, 1.0, v159
	v_rcp_f32_e32 v0, v0
	v_rcp_f32_e32 v159, v159
	v_add_f32_e32 v165, v26, v138
	v_add_f32_e32 v167, v27, v139
	v_add_f32_e32 v169, v28, v140
	v_add_f32_e32 v181, v29, v141
	v_mul_f32_e32 v161, 0xbfb8aa3b, v161
	v_mul_f32_e32 v163, 0xbfb8aa3b, v163
	v_mul_f32_e32 v165, 0xbfb8aa3b, v165
	v_mul_f32_e32 v167, 0xbfb8aa3b, v167
	v_mul_f32_e32 v169, 0xbfb8aa3b, v169
	v_mul_f32_e32 v181, 0xbfb8aa3b, v181
	v_cvt_pk_bf16_f32 v182, v0, v159
	v_add_f32_e32 v0, v22, v134
	v_add_f32_e32 v159, v23, v135
	v_exp_f32_e32 v161, v161
	v_exp_f32_e32 v163, v163
	v_exp_f32_e32 v165, v165
	v_exp_f32_e32 v167, v167
	v_exp_f32_e32 v169, v169
	v_exp_f32_e32 v181, v181
	v_mul_f32_e32 v0, 0xbfb8aa3b, v0
	v_mul_f32_e32 v159, 0xbfb8aa3b, v159
	v_exp_f32_e32 v0, v0
	v_exp_f32_e32 v159, v159
	v_add_f32_e32 v161, 1.0, v161
	v_add_f32_e32 v163, 1.0, v163
	v_add_f32_e32 v165, 1.0, v165
	v_add_f32_e32 v167, 1.0, v167
	v_add_f32_e32 v169, 1.0, v169
	v_add_f32_e32 v181, 1.0, v181
	v_add_f32_e32 v138, v10, v138
	v_rcp_f32_e32 v161, v161
	v_rcp_f32_e32 v163, v163
	v_rcp_f32_e32 v165, v165
	v_rcp_f32_e32 v167, v167
	v_rcp_f32_e32 v169, v169
	v_rcp_f32_e32 v181, v181
	v_add_f32_e32 v0, 1.0, v0
	v_add_f32_e32 v159, 1.0, v159
	v_mul_f32_e32 v138, 0xbfb8aa3b, v138
	v_rcp_f32_e32 v0, v0
	v_rcp_f32_e32 v159, v159
	v_exp_f32_e32 v138, v138
	v_lshl_add_u64 v[174:175], v[174:175], 0, v[172:173]
	v_cvt_pk_bf16_f32 v183, v161, v163
	v_cvt_pk_bf16_f32 v184, v165, v167
	v_cvt_pk_bf16_f32 v185, v169, v181
	global_store_dwordx4 v[174:175], v[182:185], off sc1
	v_add_f32_e32 v138, 1.0, v138
	v_add_f32_e32 v161, v24, v136
	v_cvt_pk_bf16_f32 v182, v0, v159
	v_add_u32_e32 v0, 0xb0, v158
	v_mad_i64_i32 v[170:171], s[0:1], v0, s2, v[170:171]
	v_add_f32_e32 v0, v14, v142
	v_add_f32_e32 v142, v15, v143
	v_add_f32_e32 v143, v16, v144
	v_add_f32_e32 v144, v17, v145
	v_rcp_f32_e32 v145, v138
	v_add_f32_e32 v138, v11, v139
	v_mul_f32_e32 v138, 0xbfb8aa3b, v138
	v_exp_f32_e32 v138, v138
	v_add_f32_e32 v163, v25, v137
	v_mul_f32_e32 v161, 0xbfb8aa3b, v161
	v_mul_f32_e32 v163, 0xbfb8aa3b, v163
	v_exp_f32_e32 v161, v161
	v_exp_f32_e32 v163, v163
	v_add_f32_e32 v138, 1.0, v138
	v_rcp_f32_e32 v159, v138
	v_add_f32_e32 v138, v12, v140
	v_mul_f32_e32 v138, 0xbfb8aa3b, v138
	v_add_f32_e32 v161, 1.0, v161
	v_add_f32_e32 v163, 1.0, v163
	v_exp_f32_e32 v138, v138
	v_rcp_f32_e32 v161, v161
	v_rcp_f32_e32 v163, v163
	v_mul_f32_e32 v0, 0xbfb8aa3b, v0
	v_mul_f32_e32 v142, 0xbfb8aa3b, v142
	v_exp_f32_e32 v0, v0
	v_exp_f32_e32 v142, v142
	v_add_f32_e32 v138, 1.0, v138
	v_add_f32_e32 v165, v18, v130
	v_cvt_pk_bf16_f32 v183, v161, v163
	v_rcp_f32_e32 v161, v138
	v_add_f32_e32 v138, v13, v141
	v_add_f32_e32 v130, v2, v130
	v_mul_f32_e32 v138, 0xbfb8aa3b, v138
	v_mul_f32_e32 v130, 0xbfb8aa3b, v130
	v_add_f32_e32 v0, 1.0, v0
	v_add_f32_e32 v142, 1.0, v142
	v_exp_f32_e32 v138, v138
	v_exp_f32_e32 v130, v130
	v_rcp_f32_e32 v0, v0
	v_rcp_f32_e32 v142, v142
	v_mul_f32_e32 v143, 0xbfb8aa3b, v143
	v_mul_f32_e32 v144, 0xbfb8aa3b, v144
	v_exp_f32_e32 v143, v143
	v_exp_f32_e32 v144, v144
	v_add_f32_e32 v138, 1.0, v138
; __device__ __forceinline__ unsigned cvt_pk_bf16(float lo, float hi) { f32x2 v = {lo, hi}; bf16x2_t b = __builtin_convertvector(v, bf16x2_t); return __builtin_bit_cast(unsigned, b); }
;     __device__ __forceinline__ void operator()(ACC_T, const Unit& u, int wr, int wc, int fr, int fq) const {
;     ...
;         if (u.pn < 14) {
;             float sc = 1.f; if (u.pn < 2 || u.pn == 6 || u.pn == 7) sc = 0.125f * LOG2E; else if (u.pn >= 12) sc = 0.08838834764831845f * LOG2E;
;             const int col0 = u.pn * BM + cw;
; #pragma unroll
;             for (int ai = 0; ai < 2; ++ai)
; #pragma unroll
;                 for (int m = 0; m < 4; ++m) { bf16_t* rowp = P + (size_t)(row0 + ai * HALF + m * 16) * PW + col0;
; #pragma unroll
;                     for (int bj = 0; bj < 2; ++bj) { const f32x4 v0 = acc[ai][bj][m][0] * sc, v1 = acc[ai][bj][m][1] * sc;
;                         u32x4 w; w.x = cvt_pk_bf16(v0[0], v0[1]); w.y = cvt_pk_bf16(v0[2], v0[3]); w.z = cvt_pk_bf16(v1[0], v1[1]); w.w = cvt_pk_bf16(v1[2], v1[3]);
;                         *(u32x4*)(rowp + bj * HALF) = w;
;                         if (u.pn == 8 || u.pn == 9) {
;                             float q = (v0[0] * v0[0] + v0[1] * v0[1]) + (v0[2] * v0[2] + v0[3] * v0[3]) + (v1[0] * v1[0] + v1[1] * v1[1]) + (v1[2] * v1[2] + v1[3] * v1[3]);
;                             q += __shfl_xor(q, 16); q += __shfl_xor(q, 32);
;                             if (fq == 0) __hip_atomic_fetch_add(kn2 + (size_t)((u.pn - 8) * 4 + bj * 2 + (wc >> 1)) * T + (row0 + ai * HALF + m * 16), q, __ATOMIC_RELAXED, __HIP_MEMORY_SCOPE_AGENT); } } }
;     ...
;             for (int ai = 0; ai < 2; ++ai)
; #pragma unroll
;                 for (int m = 0; m < 4; ++m) { bf16_t* rowp = Gt + (size_t)(row0 + ai * HALF + m * 16) * GW + col0;
; #pragma unroll
;                     for (int bj = 0; bj < 2; ++bj) { float r[8];
; #pragma unroll
;                         for (int n = 0; n < 2; ++n)
; #pragma unroll
;                             for (int e = 0; e < 4; ++e) { const float x = acc[ai][bj][m][n][e] + bv[bj][n][e]; r[n * 4 + e] = fast_rcp(1.f + fast_exp2(-x * LOG2E)); }
;                         u32x4 w; w.x = cvt_pk_bf16(r[0], r[1]); w.y = cvt_pk_bf16(r[2], r[3]); w.z = cvt_pk_bf16(r[4], r[5]); w.w = cvt_pk_bf16(r[6], r[7]);
;                         *(u32x4*)(rowp + bj * HALF) = w; } }
	v_add_f32_e32 v130, 1.0, v130
	v_rcp_f32_e32 v141, v138
	v_cvt_pk_bf16_f32 v138, v0, v142
	v_add_f32_e32 v0, v6, v134
	v_add_f32_e32 v134, v7, v135
	v_add_f32_e32 v135, v8, v136
	v_add_f32_e32 v136, v9, v137
	v_rcp_f32_e32 v137, v130
	v_add_f32_e32 v130, v3, v131
	v_add_f32_e32 v143, 1.0, v143
	v_add_f32_e32 v144, 1.0, v144
	v_mul_f32_e32 v130, 0xbfb8aa3b, v130
	v_rcp_f32_e32 v143, v143
	v_rcp_f32_e32 v144, v144
	v_exp_f32_e32 v130, v130
	v_lshl_add_u64 v[170:171], v[170:171], 0, v[172:173]
	v_cvt_pk_bf16_f32 v140, v145, v159
	v_cvt_pk_bf16_f32 v139, v143, v144
	v_cvt_pk_bf16_f32 v141, v161, v141
	v_add_f32_e32 v130, 1.0, v130
	global_store_dwordx4 v[170:171], v[138:141], off sc1
	v_add_f32_e32 v167, v19, v131
	v_add_f32_e32 v169, v20, v132
	v_rcp_f32_e32 v138, v130
	v_add_f32_e32 v130, v4, v132
	v_mul_f32_e32 v130, 0xbfb8aa3b, v130
	v_exp_f32_e32 v130, v130
	v_add_f32_e32 v181, v21, v133
	v_mul_f32_e32 v165, 0xbfb8aa3b, v165
	v_mul_f32_e32 v167, 0xbfb8aa3b, v167
	v_add_f32_e32 v130, 1.0, v130
	v_rcp_f32_e32 v139, v130
	v_add_f32_e32 v130, v5, v133
	v_mul_f32_e32 v169, 0xbfb8aa3b, v169
	v_mul_f32_e32 v181, 0xbfb8aa3b, v181
	v_mul_f32_e32 v0, 0xbfb8aa3b, v0
	v_mul_f32_e32 v134, 0xbfb8aa3b, v134
	v_mul_f32_e32 v135, 0xbfb8aa3b, v135
	v_mul_f32_e32 v136, 0xbfb8aa3b, v136
	v_mul_f32_e32 v130, 0xbfb8aa3b, v130
	v_exp_f32_e32 v165, v165
	v_exp_f32_e32 v167, v167
	v_exp_f32_e32 v169, v169
	v_exp_f32_e32 v181, v181
	v_exp_f32_e32 v0, v0
	v_exp_f32_e32 v134, v134
	v_exp_f32_e32 v135, v135
	v_exp_f32_e32 v136, v136
	v_exp_f32_e32 v130, v130
	v_add_f32_e32 v165, 1.0, v165
	v_add_f32_e32 v167, 1.0, v167
	v_add_f32_e32 v169, 1.0, v169
	v_add_f32_e32 v181, 1.0, v181
	v_add_f32_e32 v0, 1.0, v0
	v_add_f32_e32 v134, 1.0, v134
	v_add_f32_e32 v135, 1.0, v135
	v_add_f32_e32 v136, 1.0, v136
	v_add_f32_e32 v130, 1.0, v130
	v_rcp_f32_e32 v165, v165
	v_rcp_f32_e32 v167, v167
	v_rcp_f32_e32 v169, v169
	v_rcp_f32_e32 v181, v181
	v_rcp_f32_e32 v0, v0
	v_rcp_f32_e32 v134, v134
	v_rcp_f32_e32 v135, v135
	v_rcp_f32_e32 v136, v136
	v_rcp_f32_e32 v133, v130
	v_cvt_pk_bf16_f32 v184, v165, v167
	v_cvt_pk_bf16_f32 v185, v169, v181
	v_cvt_pk_bf16_f32 v130, v0, v134
	v_cvt_pk_bf16_f32 v131, v135, v136
	v_cvt_pk_bf16_f32 v132, v137, v138
	v_cvt_pk_bf16_f32 v133, v139, v133
	global_store_dwordx4 v[174:175], v[182:185], off offset:256 sc1
	global_store_dwordx4 v[170:171], v[130:133], off offset:256 sc1
	s_mov_b64 s[0:1], 0
.LBB0_305:
	s_andn2_b64 vcc, exec, s[0:1]
	s_cbranch_vccnz .LBB0_370
	s_cmp_lt_i32 s40, 2
	s_cselect_b64 s[0:1], -1, 0
	s_and_b32 s14, s40, -2
	s_cmp_eq_u32 s14, 6
	s_cselect_b64 s[2:3], -1, 0
	s_or_b64 vcc, s[0:1], s[2:3]
	s_cmp_gt_u32 s40, 11
	s_cselect_b64 s[0:1], -1, 0
	s_cmp_eq_u32 s14, 8
	v_cndmask_b32_e64 v0, 1.0, v227, s[0:1]
	s_cselect_b64 s[0:1], -1, 0
	s_lshl_b32 s2, s40, 2
	s_add_i32 s2, s2, s56
	s_cmp_lg_u32 s14, 8
	v_readlane_b32 s14, v251, 56
	v_readlane_b32 s15, v251, 57
	v_cndmask_b32_e32 v130, v0, v231, vcc
	v_lshl_or_b32 v132, s40, 8, v178
	v_mov_b64_e32 v[134:135], s[14:15]
	s_movk_i32 s3, 0x1c00
	v_ashrrev_i32_e32 v133, 31, v132
	v_mad_i64_i32 v[134:135], s[14:15], v158, s3, v[134:135]
	v_pk_mul_f32 v[128:129], v[130:131], v[128:129] op_sel_hi:[0,1]
	v_pk_mul_f32 v[126:127], v[130:131], v[126:127] op_sel_hi:[0,1]
	v_pk_mul_f32 v[124:125], v[130:131], v[124:125] op_sel_hi:[0,1]
	v_pk_mul_f32 v[122:123], v[130:131], v[122:123] op_sel_hi:[0,1]
	v_ashrrev_i32_e32 v159, 31, v158
	v_lshl_add_u64 v[134:135], v[132:133], 1, v[134:135]
	v_cvt_pk_bf16_f32 v136, v126, v127
	v_cvt_pk_bf16_f32 v137, v128, v129
	v_cvt_pk_bf16_f32 v138, v122, v123
	v_cvt_pk_bf16_f32 v139, v124, v125
	global_store_dwordx4 v[134:135], v[136:139], off sc1
	s_cbranch_scc1 .LBB0_310
	v_mul_f32_e32 v0, v127, v127
	v_fmac_f32_e32 v0, v126, v126
	v_mul_f32_e32 v126, v129, v129
	v_fmac_f32_e32 v126, v128, v128
	v_mul_f32_e32 v123, v123, v123
	v_add_f32_e32 v0, v0, v126
	v_fmac_f32_e32 v123, v122, v122
	v_mul_f32_e32 v122, v125, v125
	v_add_f32_e32 v0, v0, v123
	v_fmac_f32_e32 v122, v124, v124
	v_and_b32_e32 v123, 64, v230
	v_add_f32_e32 v0, v122, v0
	v_xor_b32_e32 v122, 16, v230
	v_add_u32_e32 v123, 64, v123
	v_cmp_lt_i32_e32 vcc, v122, v123
	s_nop 1
	v_cndmask_b32_e32 v122, v230, v122, vcc
	v_lshlrev_b32_e32 v122, 2, v122
	ds_bpermute_b32 v122, v122, v0
	s_waitcnt lgkmcnt(0)
	v_add_f32_e32 v0, v0, v122
	v_xor_b32_e32 v122, 32, v230
	v_cmp_lt_i32_e32 vcc, v122, v123
	s_nop 1
	v_cndmask_b32_e32 v122, v230, v122, vcc
	v_lshlrev_b32_e32 v122, 2, v122
	ds_bpermute_b32 v122, v122, v0
	s_and_saveexec_b64 s[14:15], s[36:37]
	s_cbranch_execz .LBB0_309
	s_lshl_b32 s3, s2, 16
	v_readlane_b32 s18, v252, 17
	s_add_u32 s18, s18, s3
	v_readlane_b32 s3, v252, 18
	s_addc_u32 s19, s3, 0
	v_lshl_add_u64 v[124:125], v[158:159], 2, s[18:19]
	s_waitcnt lgkmcnt(0)
	v_add_f32_e32 v0, v0, v122
	global_atomic_add_f32 v[124:125], v0, off

; __device__ __forceinline__ unsigned cvt_pk_bf16(float lo, float hi) { f32x2 v = {lo, hi}; bf16x2_t b = __builtin_convertvector(v, bf16x2_t); return __builtin_bit_cast(unsigned, b); }
;     __device__ __forceinline__ void operator()(ACC_T, const Unit& u, int wr, int wc, int fr, int fq) const {
;     ...
;             for (int ai = 0; ai < 2; ++ai)
; #pragma unroll
;                 for (int m = 0; m < 4; ++m) { bf16_t* rowp = P + (size_t)(row0 + ai * HALF + m * 16) * PW + col0;
; #pragma unroll
;                     for (int bj = 0; bj < 2; ++bj) { const f32x4 v0 = acc[ai][bj][m][0] * sc, v1 = acc[ai][bj][m][1] * sc;
;                         u32x4 w; w.x = cvt_pk_bf16(v0[0], v0[1]); w.y = cvt_pk_bf16(v0[2], v0[3]); w.z = cvt_pk_bf16(v1[0], v1[1]); w.w = cvt_pk_bf16(v1[2], v1[3]);
;                         *(u32x4*)(rowp + bj * HALF) = w;
;                         if (u.pn == 8 || u.pn == 9) {
;                             float q = (v0[0] * v0[0] + v0[1] * v0[1]) + (v0[2] * v0[2] + v0[3] * v0[3]) + (v1[0] * v1[0] + v1[1] * v1[1]) + (v1[2] * v1[2] + v1[3] * v1[3]);
;                             q += __shfl_xor(q, 16); q += __shfl_xor(q, 32);
;                             if (fq == 0) __hip_atomic_fetch_add(kn2 + (size_t)((u.pn - 8) * 4 + bj * 2 + (wc >> 1)) * T + (row0 + ai * HALF + m * 16), q, __ATOMIC_RELAXED, __HIP_MEMORY_SCOPE_AGENT); } } }
.LBB0_310:
	v_mov_b32_e32 v131, v130
	s_waitcnt lgkmcnt(0)
	v_mov_b32_e32 v122, v130
	v_mov_b32_e32 v123, v130
	v_pk_mul_f32 v[120:121], v[122:123], v[120:121]
	v_pk_mul_f32 v[118:119], v[130:131], v[118:119]
	v_pk_mul_f32 v[116:117], v[122:123], v[116:117]
	v_pk_mul_f32 v[114:115], v[130:131], v[114:115]
	v_cndmask_b32_e64 v0, 0, 1, s[0:1]
	v_cvt_pk_bf16_f32 v124, v118, v119
	v_cvt_pk_bf16_f32 v125, v120, v121
	v_cvt_pk_bf16_f32 v126, v114, v115
	v_cvt_pk_bf16_f32 v127, v116, v117
	v_cmp_ne_u32_e64 s[40:41], 1, v0
	s_andn2_b64 vcc, exec, s[0:1]
	global_store_dwordx4 v[134:135], v[124:127], off offset:256 sc1
	s_cbranch_vccnz .LBB0_314
	v_mul_f32_e32 v0, v119, v119
	v_fmac_f32_e32 v0, v118, v118
	v_mul_f32_e32 v118, v121, v121
	v_fmac_f32_e32 v118, v120, v120
	v_mul_f32_e32 v115, v115, v115
	v_add_f32_e32 v0, v0, v118
	v_fmac_f32_e32 v115, v114, v114
	v_mul_f32_e32 v114, v117, v117
	v_add_f32_e32 v0, v0, v115
	v_fmac_f32_e32 v114, v116, v116
	v_and_b32_e32 v115, 64, v230
	v_add_f32_e32 v0, v114, v0
	v_xor_b32_e32 v114, 16, v230
	v_add_u32_e32 v115, 64, v115
	v_cmp_lt_i32_e32 vcc, v114, v115
	s_nop 1
	v_cndmask_b32_e32 v114, v230, v114, vcc
	v_lshlrev_b32_e32 v114, 2, v114
	ds_bpermute_b32 v114, v114, v0
	s_waitcnt lgkmcnt(0)
	v_add_f32_e32 v0, v0, v114
	v_xor_b32_e32 v114, 32, v230
	v_cmp_lt_i32_e32 vcc, v114, v115
	s_nop 1
	v_cndmask_b32_e32 v114, v230, v114, vcc
	v_lshlrev_b32_e32 v114, 2, v114
	ds_bpermute_b32 v114, v114, v0
	s_and_saveexec_b64 s[0:1], s[36:37]
	s_cbranch_execz .LBB0_313
	s_lshl_b32 s3, s2, 16
	v_readlane_b32 s14, v252, 17
	s_add_u32 s14, s14, s3
	v_readlane_b32 s3, v252, 18
	s_addc_u32 s15, s3, 0
	v_lshl_add_u64 v[116:117], v[158:159], 2, s[14:15]
	s_waitcnt lgkmcnt(0)
	v_add_f32_e32 v0, v0, v114
	v_add_co_u32_e32 v114, vcc, 0x20000, v116
	s_nop 1
	v_addc_co_u32_e32 v115, vcc, 0, v117, vcc
	global_atomic_add_f32 v[114:115], v0, off

; __device__ __forceinline__ unsigned cvt_pk_bf16(float lo, float hi) { f32x2 v = {lo, hi}; bf16x2_t b = __builtin_convertvector(v, bf16x2_t); return __builtin_bit_cast(unsigned, b); }
;     __device__ __forceinline__ void operator()(ACC_T, const Unit& u, int wr, int wc, int fr, int fq) const {
;     ...
;             for (int ai = 0; ai < 2; ++ai)
; #pragma unroll
;                 for (int m = 0; m < 4; ++m) { bf16_t* rowp = P + (size_t)(row0 + ai * HALF + m * 16) * PW + col0;
; #pragma unroll
;                     for (int bj = 0; bj < 2; ++bj) { const f32x4 v0 = acc[ai][bj][m][0] * sc, v1 = acc[ai][bj][m][1] * sc;
;                         u32x4 w; w.x = cvt_pk_bf16(v0[0], v0[1]); w.y = cvt_pk_bf16(v0[2], v0[3]); w.z = cvt_pk_bf16(v1[0], v1[1]); w.w = cvt_pk_bf16(v1[2], v1[3]);
;                         *(u32x4*)(rowp + bj * HALF) = w;
;                         if (u.pn == 8 || u.pn == 9) {
;                             float q = (v0[0] * v0[0] + v0[1] * v0[1]) + (v0[2] * v0[2] + v0[3] * v0[3]) + (v1[0] * v1[0] + v1[1] * v1[1]) + (v1[2] * v1[2] + v1[3] * v1[3]);
;                             q += __shfl_xor(q, 16); q += __shfl_xor(q, 32);
;                             if (fq == 0) __hip_atomic_fetch_add(kn2 + (size_t)((u.pn - 8) * 4 + bj * 2 + (wc >> 1)) * T + (row0 + ai * HALF + m * 16), q, __ATOMIC_RELAXED, __HIP_MEMORY_SCOPE_AGENT); } } }
.LBB0_314:
	v_readlane_b32 s0, v251, 56
	v_readlane_b32 s1, v251, 57
	v_pk_mul_f32 v[112:113], v[122:123], v[112:113]
	v_pk_mul_f32 v[110:111], v[130:131], v[110:111]
	s_waitcnt lgkmcnt(0)
	v_mov_b64_e32 v[114:115], s[0:1]
	s_movk_i32 s0, 0x1c00
	v_mad_i64_i32 v[114:115], s[0:1], v168, s0, v[114:115]
	v_pk_mul_f32 v[108:109], v[122:123], v[108:109]
	v_pk_mul_f32 v[106:107], v[130:131], v[106:107]
	v_lshl_add_u64 v[114:115], v[132:133], 1, v[114:115]
	v_cvt_pk_bf16_f32 v116, v110, v111
	v_cvt_pk_bf16_f32 v117, v112, v113
	v_cvt_pk_bf16_f32 v118, v106, v107
	v_cvt_pk_bf16_f32 v119, v108, v109
	s_and_b64 vcc, exec, s[40:41]
	global_store_dwordx4 v[114:115], v[116:119], off sc1
	s_cbranch_vccnz .LBB0_318
	v_mul_f32_e32 v0, v111, v111
	v_fmac_f32_e32 v0, v110, v110
	v_mul_f32_e32 v110, v113, v113
	v_fmac_f32_e32 v110, v112, v112
	v_mul_f32_e32 v107, v107, v107
	v_add_f32_e32 v0, v0, v110
	v_fmac_f32_e32 v107, v106, v106
	v_mul_f32_e32 v106, v109, v109
	v_add_f32_e32 v0, v0, v107
	v_fmac_f32_e32 v106, v108, v108
	v_and_b32_e32 v107, 64, v230
	v_add_f32_e32 v0, v106, v0
	v_xor_b32_e32 v106, 16, v230
	v_add_u32_e32 v107, 64, v107
	v_cmp_lt_i32_e32 vcc, v106, v107
	s_nop 1
	v_cndmask_b32_e32 v106, v230, v106, vcc
	v_lshlrev_b32_e32 v106, 2, v106
	ds_bpermute_b32 v106, v106, v0
	s_waitcnt lgkmcnt(0)
	v_add_f32_e32 v0, v0, v106
	v_xor_b32_e32 v106, 32, v230
	v_cmp_lt_i32_e32 vcc, v106, v107
	s_nop 1
	v_cndmask_b32_e32 v106, v230, v106, vcc
	v_lshlrev_b32_e32 v106, 2, v106
	ds_bpermute_b32 v106, v106, v0
	s_and_saveexec_b64 s[0:1], s[36:37]
	s_cbranch_execz .LBB0_317
	s_lshl_b32 s3, s2, 16
	v_readlane_b32 s14, v252, 17
	s_add_u32 s14, s14, s3
	v_readlane_b32 s3, v252, 18
	s_addc_u32 s15, s3, 0
	v_lshl_add_u64 v[108:109], v[158:159], 2, s[14:15]
	s_waitcnt lgkmcnt(0)
	v_add_f32_e32 v0, v0, v106
	global_atomic_add_f32 v[108:109], v0, off offset:64

; __device__ __forceinline__ unsigned cvt_pk_bf16(float lo, float hi) { f32x2 v = {lo, hi}; bf16x2_t b = __builtin_convertvector(v, bf16x2_t); return __builtin_bit_cast(unsigned, b); }
;     __device__ __forceinline__ void operator()(ACC_T, const Unit& u, int wr, int wc, int fr, int fq) const {
;     ...
;             for (int ai = 0; ai < 2; ++ai)
; #pragma unroll
;                 for (int m = 0; m < 4; ++m) { bf16_t* rowp = P + (size_t)(row0 + ai * HALF + m * 16) * PW + col0;
; #pragma unroll
;                     for (int bj = 0; bj < 2; ++bj) { const f32x4 v0 = acc[ai][bj][m][0] * sc, v1 = acc[ai][bj][m][1] * sc;
;                         u32x4 w; w.x = cvt_pk_bf16(v0[0], v0[1]); w.y = cvt_pk_bf16(v0[2], v0[3]); w.z = cvt_pk_bf16(v1[0], v1[1]); w.w = cvt_pk_bf16(v1[2], v1[3]);
;                         *(u32x4*)(rowp + bj * HALF) = w;
;                         if (u.pn == 8 || u.pn == 9) {
;                             float q = (v0[0] * v0[0] + v0[1] * v0[1]) + (v0[2] * v0[2] + v0[3] * v0[3]) + (v1[0] * v1[0] + v1[1] * v1[1]) + (v1[2] * v1[2] + v1[3] * v1[3]);
;                             q += __shfl_xor(q, 16); q += __shfl_xor(q, 32);
;                             if (fq == 0) __hip_atomic_fetch_add(kn2 + (size_t)((u.pn - 8) * 4 + bj * 2 + (wc >> 1)) * T + (row0 + ai * HALF + m * 16), q, __ATOMIC_RELAXED, __HIP_MEMORY_SCOPE_AGENT); } } }
.LBB0_318:
	s_waitcnt lgkmcnt(0)
	v_mov_b32_e32 v106, v130
	v_mov_b32_e32 v107, v130
	v_pk_mul_f32 v[104:105], v[106:107], v[104:105]
	v_pk_mul_f32 v[102:103], v[130:131], v[102:103]
	v_pk_mul_f32 v[100:101], v[106:107], v[100:101]
	v_pk_mul_f32 v[98:99], v[130:131], v[98:99]
	v_cvt_pk_bf16_f32 v108, v102, v103
	v_cvt_pk_bf16_f32 v109, v104, v105
	v_cvt_pk_bf16_f32 v110, v98, v99
	v_cvt_pk_bf16_f32 v111, v100, v101
	s_and_b64 vcc, exec, s[40:41]
	global_store_dwordx4 v[114:115], v[108:111], off offset:256 sc1
	s_cbranch_vccnz .LBB0_322
	v_mul_f32_e32 v0, v103, v103
	v_fmac_f32_e32 v0, v102, v102
	v_mul_f32_e32 v102, v105, v105
	v_fmac_f32_e32 v102, v104, v104
	v_mul_f32_e32 v99, v99, v99
	v_add_f32_e32 v0, v0, v102
	v_fmac_f32_e32 v99, v98, v98
	v_mul_f32_e32 v98, v101, v101
	v_add_f32_e32 v0, v0, v99
	v_fmac_f32_e32 v98, v100, v100
	v_and_b32_e32 v99, 64, v230
	v_add_f32_e32 v0, v98, v0
	v_xor_b32_e32 v98, 16, v230
	v_add_u32_e32 v99, 64, v99
	v_cmp_lt_i32_e32 vcc, v98, v99
	s_nop 1
	v_cndmask_b32_e32 v98, v230, v98, vcc
	v_lshlrev_b32_e32 v98, 2, v98
	ds_bpermute_b32 v98, v98, v0
	s_waitcnt lgkmcnt(0)
	v_add_f32_e32 v0, v0, v98
	v_xor_b32_e32 v98, 32, v230
	v_cmp_lt_i32_e32 vcc, v98, v99
	s_nop 1
	v_cndmask_b32_e32 v98, v230, v98, vcc
	v_lshlrev_b32_e32 v98, 2, v98
	ds_bpermute_b32 v98, v98, v0
	s_and_saveexec_b64 s[0:1], s[36:37]
	s_cbranch_execz .LBB0_321
	s_lshl_b32 s3, s2, 16
	v_readlane_b32 s14, v252, 17
	s_add_u32 s14, s14, s3
	v_readlane_b32 s3, v252, 18
	v_ashrrev_i32_e32 v169, 31, v168
	s_addc_u32 s15, s3, 0
	v_lshl_add_u64 v[100:101], v[168:169], 2, s[14:15]
	s_waitcnt lgkmcnt(0)
	v_add_f32_e32 v0, v0, v98
	v_add_co_u32_e32 v98, vcc, 0x20000, v100
	s_nop 1
	v_addc_co_u32_e32 v99, vcc, 0, v101, vcc
	global_atomic_add_f32 v[98:99], v0, off

; __device__ __forceinline__ unsigned cvt_pk_bf16(float lo, float hi) { f32x2 v = {lo, hi}; bf16x2_t b = __builtin_convertvector(v, bf16x2_t); return __builtin_bit_cast(unsigned, b); }
;     __device__ __forceinline__ void operator()(ACC_T, const Unit& u, int wr, int wc, int fr, int fq) const {
;     ...
;             for (int ai = 0; ai < 2; ++ai)
; #pragma unroll
;                 for (int m = 0; m < 4; ++m) { bf16_t* rowp = P + (size_t)(row0 + ai * HALF + m * 16) * PW + col0;
; #pragma unroll
;                     for (int bj = 0; bj < 2; ++bj) { const f32x4 v0 = acc[ai][bj][m][0] * sc, v1 = acc[ai][bj][m][1] * sc;
;                         u32x4 w; w.x = cvt_pk_bf16(v0[0], v0[1]); w.y = cvt_pk_bf16(v0[2], v0[3]); w.z = cvt_pk_bf16(v1[0], v1[1]); w.w = cvt_pk_bf16(v1[2], v1[3]);
;                         *(u32x4*)(rowp + bj * HALF) = w;
;                         if (u.pn == 8 || u.pn == 9) {
;                             float q = (v0[0] * v0[0] + v0[1] * v0[1]) + (v0[2] * v0[2] + v0[3] * v0[3]) + (v1[0] * v1[0] + v1[1] * v1[1]) + (v1[2] * v1[2] + v1[3] * v1[3]);
;                             q += __shfl_xor(q, 16); q += __shfl_xor(q, 32);
;                             if (fq == 0) __hip_atomic_fetch_add(kn2 + (size_t)((u.pn - 8) * 4 + bj * 2 + (wc >> 1)) * T + (row0 + ai * HALF + m * 16), q, __ATOMIC_RELAXED, __HIP_MEMORY_SCOPE_AGENT); } } }
.LBB0_322:
	v_readlane_b32 s0, v251, 56
	v_readlane_b32 s1, v251, 57
	v_pk_mul_f32 v[96:97], v[106:107], v[96:97]
	v_pk_mul_f32 v[94:95], v[130:131], v[94:95]
	s_waitcnt lgkmcnt(0)
	v_mov_b64_e32 v[98:99], s[0:1]
	s_movk_i32 s0, 0x1c00
	v_mad_i64_i32 v[98:99], s[0:1], v166, s0, v[98:99]
	v_pk_mul_f32 v[92:93], v[106:107], v[92:93]
	v_pk_mul_f32 v[90:91], v[130:131], v[90:91]
	v_lshl_add_u64 v[98:99], v[132:133], 1, v[98:99]
	v_cvt_pk_bf16_f32 v100, v94, v95
	v_cvt_pk_bf16_f32 v101, v96, v97
	v_cvt_pk_bf16_f32 v102, v90, v91
	v_cvt_pk_bf16_f32 v103, v92, v93
	s_and_b64 vcc, exec, s[40:41]
	global_store_dwordx4 v[98:99], v[100:103], off sc1
	s_cbranch_vccnz .LBB0_326
	v_mul_f32_e32 v0, v95, v95
	v_fmac_f32_e32 v0, v94, v94
	v_mul_f32_e32 v94, v97, v97
	v_fmac_f32_e32 v94, v96, v96
	v_mul_f32_e32 v91, v91, v91
	v_add_f32_e32 v0, v0, v94
	v_fmac_f32_e32 v91, v90, v90
	v_mul_f32_e32 v90, v93, v93
	v_add_f32_e32 v0, v0, v91
	v_fmac_f32_e32 v90, v92, v92
	v_and_b32_e32 v91, 64, v230
	v_add_f32_e32 v0, v90, v0
	v_xor_b32_e32 v90, 16, v230
	v_add_u32_e32 v91, 64, v91
	v_cmp_lt_i32_e32 vcc, v90, v91
	s_nop 1
	v_cndmask_b32_e32 v90, v230, v90, vcc
	v_lshlrev_b32_e32 v90, 2, v90
	ds_bpermute_b32 v90, v90, v0
	s_waitcnt lgkmcnt(0)
	v_add_f32_e32 v0, v0, v90
	v_xor_b32_e32 v90, 32, v230
	v_cmp_lt_i32_e32 vcc, v90, v91
	s_nop 1
	v_cndmask_b32_e32 v90, v230, v90, vcc
	v_lshlrev_b32_e32 v90, 2, v90
	ds_bpermute_b32 v90, v90, v0
	s_and_saveexec_b64 s[0:1], s[36:37]
	s_cbranch_execz .LBB0_325
	s_lshl_b32 s3, s2, 16
	v_readlane_b32 s14, v252, 17
	s_add_u32 s14, s14, s3
	v_readlane_b32 s3, v252, 18
	s_addc_u32 s15, s3, 0
	v_lshl_add_u64 v[92:93], v[158:159], 2, s[14:15]
	s_waitcnt lgkmcnt(0)
	v_add_f32_e32 v0, v0, v90
	global_atomic_add_f32 v[92:93], v0, off offset:128

; __device__ __forceinline__ unsigned cvt_pk_bf16(float lo, float hi) { f32x2 v = {lo, hi}; bf16x2_t b = __builtin_convertvector(v, bf16x2_t); return __builtin_bit_cast(unsigned, b); }
;     __device__ __forceinline__ void operator()(ACC_T, const Unit& u, int wr, int wc, int fr, int fq) const {
;     ...
;             for (int ai = 0; ai < 2; ++ai)
; #pragma unroll
;                 for (int m = 0; m < 4; ++m) { bf16_t* rowp = P + (size_t)(row0 + ai * HALF + m * 16) * PW + col0;
; #pragma unroll
;                     for (int bj = 0; bj < 2; ++bj) { const f32x4 v0 = acc[ai][bj][m][0] * sc, v1 = acc[ai][bj][m][1] * sc;
;                         u32x4 w; w.x = cvt_pk_bf16(v0[0], v0[1]); w.y = cvt_pk_bf16(v0[2], v0[3]); w.z = cvt_pk_bf16(v1[0], v1[1]); w.w = cvt_pk_bf16(v1[2], v1[3]);
;                         *(u32x4*)(rowp + bj * HALF) = w;
;                         if (u.pn == 8 || u.pn == 9) {
;                             float q = (v0[0] * v0[0] + v0[1] * v0[1]) + (v0[2] * v0[2] + v0[3] * v0[3]) + (v1[0] * v1[0] + v1[1] * v1[1]) + (v1[2] * v1[2] + v1[3] * v1[3]);
;                             q += __shfl_xor(q, 16); q += __shfl_xor(q, 32);
;                             if (fq == 0) __hip_atomic_fetch_add(kn2 + (size_t)((u.pn - 8) * 4 + bj * 2 + (wc >> 1)) * T + (row0 + ai * HALF + m * 16), q, __ATOMIC_RELAXED, __HIP_MEMORY_SCOPE_AGENT); } } }
.LBB0_326:
	s_waitcnt lgkmcnt(0)
	v_mov_b32_e32 v90, v130
	v_mov_b32_e32 v91, v130
	v_pk_mul_f32 v[88:89], v[90:91], v[88:89]
	v_pk_mul_f32 v[86:87], v[130:131], v[86:87]
	v_pk_mul_f32 v[84:85], v[90:91], v[84:85]
	v_pk_mul_f32 v[82:83], v[130:131], v[82:83]
	v_cvt_pk_bf16_f32 v92, v86, v87
	v_cvt_pk_bf16_f32 v93, v88, v89
	v_cvt_pk_bf16_f32 v94, v82, v83
	v_cvt_pk_bf16_f32 v95, v84, v85
	s_and_b64 vcc, exec, s[40:41]
	global_store_dwordx4 v[98:99], v[92:95], off offset:256 sc1
	s_cbranch_vccnz .LBB0_330
	v_mul_f32_e32 v0, v87, v87
	v_fmac_f32_e32 v0, v86, v86
	v_mul_f32_e32 v86, v89, v89
	v_fmac_f32_e32 v86, v88, v88
	v_mul_f32_e32 v83, v83, v83
	v_add_f32_e32 v0, v0, v86
	v_fmac_f32_e32 v83, v82, v82
	v_mul_f32_e32 v82, v85, v85
	v_add_f32_e32 v0, v0, v83
	v_fmac_f32_e32 v82, v84, v84
	v_and_b32_e32 v83, 64, v230
	v_add_f32_e32 v0, v82, v0
	v_xor_b32_e32 v82, 16, v230
	v_add_u32_e32 v83, 64, v83
	v_cmp_lt_i32_e32 vcc, v82, v83
	s_nop 1
	v_cndmask_b32_e32 v82, v230, v82, vcc
	v_lshlrev_b32_e32 v82, 2, v82
	ds_bpermute_b32 v82, v82, v0
	s_waitcnt lgkmcnt(0)
	v_add_f32_e32 v0, v0, v82
	v_xor_b32_e32 v82, 32, v230
	v_cmp_lt_i32_e32 vcc, v82, v83
	s_nop 1
	v_cndmask_b32_e32 v82, v230, v82, vcc
	v_lshlrev_b32_e32 v82, 2, v82
	ds_bpermute_b32 v82, v82, v0
	s_and_saveexec_b64 s[0:1], s[36:37]
	s_cbranch_execz .LBB0_329
	s_lshl_b32 s3, s2, 16
	v_readlane_b32 s14, v252, 17
	s_add_u32 s14, s14, s3
	v_readlane_b32 s3, v252, 18
	v_ashrrev_i32_e32 v167, 31, v166
	s_addc_u32 s15, s3, 0
	v_lshl_add_u64 v[84:85], v[166:167], 2, s[14:15]
	s_waitcnt lgkmcnt(0)
	v_add_f32_e32 v0, v0, v82
	v_add_co_u32_e32 v82, vcc, 0x20000, v84
	s_nop 1
	v_addc_co_u32_e32 v83, vcc, 0, v85, vcc
	global_atomic_add_f32 v[82:83], v0, off

; __device__ __forceinline__ unsigned cvt_pk_bf16(float lo, float hi) { f32x2 v = {lo, hi}; bf16x2_t b = __builtin_convertvector(v, bf16x2_t); return __builtin_bit_cast(unsigned, b); }
;     __device__ __forceinline__ void operator()(ACC_T, const Unit& u, int wr, int wc, int fr, int fq) const {
;     ...
;             for (int ai = 0; ai < 2; ++ai)
; #pragma unroll
;                 for (int m = 0; m < 4; ++m) { bf16_t* rowp = P + (size_t)(row0 + ai * HALF + m * 16) * PW + col0;
; #pragma unroll
;                     for (int bj = 0; bj < 2; ++bj) { const f32x4 v0 = acc[ai][bj][m][0] * sc, v1 = acc[ai][bj][m][1] * sc;
;                         u32x4 w; w.x = cvt_pk_bf16(v0[0], v0[1]); w.y = cvt_pk_bf16(v0[2], v0[3]); w.z = cvt_pk_bf16(v1[0], v1[1]); w.w = cvt_pk_bf16(v1[2], v1[3]);
;                         *(u32x4*)(rowp + bj * HALF) = w;
;                         if (u.pn == 8 || u.pn == 9) {
;                             float q = (v0[0] * v0[0] + v0[1] * v0[1]) + (v0[2] * v0[2] + v0[3] * v0[3]) + (v1[0] * v1[0] + v1[1] * v1[1]) + (v1[2] * v1[2] + v1[3] * v1[3]);
;                             q += __shfl_xor(q, 16); q += __shfl_xor(q, 32);
;                             if (fq == 0) __hip_atomic_fetch_add(kn2 + (size_t)((u.pn - 8) * 4 + bj * 2 + (wc >> 1)) * T + (row0 + ai * HALF + m * 16), q, __ATOMIC_RELAXED, __HIP_MEMORY_SCOPE_AGENT); } } }
.LBB0_330:
	v_readlane_b32 s0, v251, 56
	v_readlane_b32 s1, v251, 57
	v_pk_mul_f32 v[80:81], v[90:91], v[80:81]
	v_pk_mul_f32 v[78:79], v[130:131], v[78:79]
	s_waitcnt lgkmcnt(0)
	v_mov_b64_e32 v[82:83], s[0:1]
	s_movk_i32 s0, 0x1c00
	v_mad_i64_i32 v[82:83], s[0:1], v164, s0, v[82:83]
	v_pk_mul_f32 v[76:77], v[90:91], v[76:77]
	v_pk_mul_f32 v[74:75], v[130:131], v[74:75]
	v_lshl_add_u64 v[82:83], v[132:133], 1, v[82:83]
	v_cvt_pk_bf16_f32 v84, v78, v79
	v_cvt_pk_bf16_f32 v85, v80, v81
	v_cvt_pk_bf16_f32 v86, v74, v75
	v_cvt_pk_bf16_f32 v87, v76, v77
	s_and_b64 vcc, exec, s[40:41]
	global_store_dwordx4 v[82:83], v[84:87], off sc1
	s_cbranch_vccnz .LBB0_334
	v_mul_f32_e32 v0, v79, v79
	v_fmac_f32_e32 v0, v78, v78
	v_mul_f32_e32 v78, v81, v81
	v_fmac_f32_e32 v78, v80, v80
	v_mul_f32_e32 v75, v75, v75
	v_add_f32_e32 v0, v0, v78
	v_fmac_f32_e32 v75, v74, v74
	v_mul_f32_e32 v74, v77, v77
	v_add_f32_e32 v0, v0, v75
	v_fmac_f32_e32 v74, v76, v76
	v_and_b32_e32 v75, 64, v230
	v_add_f32_e32 v0, v74, v0
	v_xor_b32_e32 v74, 16, v230
	v_add_u32_e32 v75, 64, v75
	v_cmp_lt_i32_e32 vcc, v74, v75
	s_nop 1
	v_cndmask_b32_e32 v74, v230, v74, vcc
	v_lshlrev_b32_e32 v74, 2, v74
	ds_bpermute_b32 v74, v74, v0
	s_waitcnt lgkmcnt(0)
	v_add_f32_e32 v0, v0, v74
	v_xor_b32_e32 v74, 32, v230
	v_cmp_lt_i32_e32 vcc, v74, v75
	s_nop 1
	v_cndmask_b32_e32 v74, v230, v74, vcc
	v_lshlrev_b32_e32 v74, 2, v74
	ds_bpermute_b32 v74, v74, v0
	s_and_saveexec_b64 s[0:1], s[36:37]
	s_cbranch_execz .LBB0_333
	s_lshl_b32 s3, s2, 16
	v_readlane_b32 s14, v252, 17
	s_add_u32 s14, s14, s3
	v_readlane_b32 s3, v252, 18
	s_addc_u32 s15, s3, 0
	v_lshl_add_u64 v[76:77], v[158:159], 2, s[14:15]
	s_waitcnt lgkmcnt(0)
	v_add_f32_e32 v0, v0, v74
	global_atomic_add_f32 v[76:77], v0, off offset:192

; __device__ __forceinline__ unsigned cvt_pk_bf16(float lo, float hi) { f32x2 v = {lo, hi}; bf16x2_t b = __builtin_convertvector(v, bf16x2_t); return __builtin_bit_cast(unsigned, b); }
;     __device__ __forceinline__ void operator()(ACC_T, const Unit& u, int wr, int wc, int fr, int fq) const {
;     ...
;             for (int ai = 0; ai < 2; ++ai)
; #pragma unroll
;                 for (int m = 0; m < 4; ++m) { bf16_t* rowp = P + (size_t)(row0 + ai * HALF + m * 16) * PW + col0;
; #pragma unroll
;                     for (int bj = 0; bj < 2; ++bj) { const f32x4 v0 = acc[ai][bj][m][0] * sc, v1 = acc[ai][bj][m][1] * sc;
;                         u32x4 w; w.x = cvt_pk_bf16(v0[0], v0[1]); w.y = cvt_pk_bf16(v0[2], v0[3]); w.z = cvt_pk_bf16(v1[0], v1[1]); w.w = cvt_pk_bf16(v1[2], v1[3]);
;                         *(u32x4*)(rowp + bj * HALF) = w;
;                         if (u.pn == 8 || u.pn == 9) {
;                             float q = (v0[0] * v0[0] + v0[1] * v0[1]) + (v0[2] * v0[2] + v0[3] * v0[3]) + (v1[0] * v1[0] + v1[1] * v1[1]) + (v1[2] * v1[2] + v1[3] * v1[3]);
;                             q += __shfl_xor(q, 16); q += __shfl_xor(q, 32);
;                             if (fq == 0) __hip_atomic_fetch_add(kn2 + (size_t)((u.pn - 8) * 4 + bj * 2 + (wc >> 1)) * T + (row0 + ai * HALF + m * 16), q, __ATOMIC_RELAXED, __HIP_MEMORY_SCOPE_AGENT); } } }
.LBB0_334:
	s_waitcnt lgkmcnt(0)
	v_mov_b32_e32 v74, v130
	v_mov_b32_e32 v75, v130
	v_pk_mul_f32 v[72:73], v[74:75], v[72:73]
	v_pk_mul_f32 v[70:71], v[130:131], v[70:71]
	v_pk_mul_f32 v[68:69], v[74:75], v[68:69]
	v_pk_mul_f32 v[66:67], v[130:131], v[66:67]
	v_cvt_pk_bf16_f32 v76, v70, v71
	v_cvt_pk_bf16_f32 v77, v72, v73
	v_cvt_pk_bf16_f32 v78, v66, v67
	v_cvt_pk_bf16_f32 v79, v68, v69
	s_and_b64 vcc, exec, s[40:41]
	global_store_dwordx4 v[82:83], v[76:79], off offset:256 sc1
	s_cbranch_vccnz .LBB0_338
	v_mul_f32_e32 v0, v71, v71
	v_fmac_f32_e32 v0, v70, v70
	v_mul_f32_e32 v70, v73, v73
	v_fmac_f32_e32 v70, v72, v72
	v_mul_f32_e32 v67, v67, v67
	v_add_f32_e32 v0, v0, v70
	v_fmac_f32_e32 v67, v66, v66
	v_mul_f32_e32 v66, v69, v69
	v_add_f32_e32 v0, v0, v67
	v_fmac_f32_e32 v66, v68, v68
	v_and_b32_e32 v67, 64, v230
	v_add_f32_e32 v0, v66, v0
	v_xor_b32_e32 v66, 16, v230
	v_add_u32_e32 v67, 64, v67
	v_cmp_lt_i32_e32 vcc, v66, v67
	s_nop 1
	v_cndmask_b32_e32 v66, v230, v66, vcc
	v_lshlrev_b32_e32 v66, 2, v66
	ds_bpermute_b32 v66, v66, v0
	s_waitcnt lgkmcnt(0)
	v_add_f32_e32 v0, v0, v66
	v_xor_b32_e32 v66, 32, v230
	v_cmp_lt_i32_e32 vcc, v66, v67
	s_nop 1
	v_cndmask_b32_e32 v66, v230, v66, vcc
	v_lshlrev_b32_e32 v66, 2, v66
	ds_bpermute_b32 v66, v66, v0
	s_and_saveexec_b64 s[0:1], s[36:37]
	s_cbranch_execz .LBB0_337
	s_lshl_b32 s3, s2, 16
	v_readlane_b32 s14, v252, 17
	s_add_u32 s14, s14, s3
	v_readlane_b32 s3, v252, 18
	v_ashrrev_i32_e32 v165, 31, v164
	s_addc_u32 s15, s3, 0
	v_lshl_add_u64 v[68:69], v[164:165], 2, s[14:15]
	s_waitcnt lgkmcnt(0)
	v_add_f32_e32 v0, v0, v66
	v_add_co_u32_e32 v66, vcc, 0x20000, v68
	s_nop 1
	v_addc_co_u32_e32 v67, vcc, 0, v69, vcc
	global_atomic_add_f32 v[66:67], v0, off

; __device__ __forceinline__ unsigned cvt_pk_bf16(float lo, float hi) { f32x2 v = {lo, hi}; bf16x2_t b = __builtin_convertvector(v, bf16x2_t); return __builtin_bit_cast(unsigned, b); }
;     __device__ __forceinline__ void operator()(ACC_T, const Unit& u, int wr, int wc, int fr, int fq) const {
;     ...
;             for (int ai = 0; ai < 2; ++ai)
; #pragma unroll
;                 for (int m = 0; m < 4; ++m) { bf16_t* rowp = P + (size_t)(row0 + ai * HALF + m * 16) * PW + col0;
; #pragma unroll
;                     for (int bj = 0; bj < 2; ++bj) { const f32x4 v0 = acc[ai][bj][m][0] * sc, v1 = acc[ai][bj][m][1] * sc;
;                         u32x4 w; w.x = cvt_pk_bf16(v0[0], v0[1]); w.y = cvt_pk_bf16(v0[2], v0[3]); w.z = cvt_pk_bf16(v1[0], v1[1]); w.w = cvt_pk_bf16(v1[2], v1[3]);
;                         *(u32x4*)(rowp + bj * HALF) = w;
;                         if (u.pn == 8 || u.pn == 9) {
;                             float q = (v0[0] * v0[0] + v0[1] * v0[1]) + (v0[2] * v0[2] + v0[3] * v0[3]) + (v1[0] * v1[0] + v1[1] * v1[1]) + (v1[2] * v1[2] + v1[3] * v1[3]);
;                             q += __shfl_xor(q, 16); q += __shfl_xor(q, 32);
;                             if (fq == 0) __hip_atomic_fetch_add(kn2 + (size_t)((u.pn - 8) * 4 + bj * 2 + (wc >> 1)) * T + (row0 + ai * HALF + m * 16), q, __ATOMIC_RELAXED, __HIP_MEMORY_SCOPE_AGENT); } } }
.LBB0_338:
	v_readlane_b32 s0, v251, 56
	v_readlane_b32 s1, v251, 57
	v_pk_mul_f32 v[64:65], v[74:75], v[64:65]
	v_pk_mul_f32 v[62:63], v[130:131], v[62:63]
	s_waitcnt lgkmcnt(0)
	v_mov_b64_e32 v[66:67], s[0:1]
	s_movk_i32 s0, 0x1c00
	v_mad_i64_i32 v[66:67], s[0:1], v162, s0, v[66:67]
	v_pk_mul_f32 v[60:61], v[74:75], v[60:61]
	v_pk_mul_f32 v[58:59], v[130:131], v[58:59]
	v_lshl_add_u64 v[66:67], v[132:133], 1, v[66:67]
	v_cvt_pk_bf16_f32 v68, v62, v63
	v_cvt_pk_bf16_f32 v69, v64, v65
	v_cvt_pk_bf16_f32 v70, v58, v59
	v_cvt_pk_bf16_f32 v71, v60, v61
	s_and_b64 vcc, exec, s[40:41]
	global_store_dwordx4 v[66:67], v[68:71], off sc1
	s_cbranch_vccnz .LBB0_342
	v_mul_f32_e32 v0, v63, v63
	v_fmac_f32_e32 v0, v62, v62
	v_mul_f32_e32 v62, v65, v65
	v_fmac_f32_e32 v62, v64, v64
	v_mul_f32_e32 v59, v59, v59
	v_add_f32_e32 v0, v0, v62
	v_fmac_f32_e32 v59, v58, v58
	v_mul_f32_e32 v58, v61, v61
	v_add_f32_e32 v0, v0, v59
	v_fmac_f32_e32 v58, v60, v60
	v_and_b32_e32 v59, 64, v230
	v_add_f32_e32 v0, v58, v0
	v_xor_b32_e32 v58, 16, v230
	v_add_u32_e32 v59, 64, v59
	v_cmp_lt_i32_e32 vcc, v58, v59
	s_nop 1
	v_cndmask_b32_e32 v58, v230, v58, vcc
	v_lshlrev_b32_e32 v58, 2, v58
	ds_bpermute_b32 v58, v58, v0
	s_waitcnt lgkmcnt(0)
	v_add_f32_e32 v0, v0, v58
	v_xor_b32_e32 v58, 32, v230
	v_cmp_lt_i32_e32 vcc, v58, v59
	s_nop 1
	v_cndmask_b32_e32 v58, v230, v58, vcc
	v_lshlrev_b32_e32 v58, 2, v58
	ds_bpermute_b32 v58, v58, v0
	s_and_saveexec_b64 s[0:1], s[36:37]
	s_cbranch_execz .LBB0_341
	s_lshl_b32 s3, s2, 16
	v_readlane_b32 s14, v252, 17
	s_add_u32 s14, s14, s3
	v_readlane_b32 s3, v252, 18
	s_addc_u32 s15, s3, 0
	v_lshl_add_u64 v[60:61], v[158:159], 2, s[14:15]
	s_waitcnt lgkmcnt(0)
	v_add_f32_e32 v0, v0, v58
	global_atomic_add_f32 v[60:61], v0, off offset:512

; __device__ __forceinline__ unsigned cvt_pk_bf16(float lo, float hi) { f32x2 v = {lo, hi}; bf16x2_t b = __builtin_convertvector(v, bf16x2_t); return __builtin_bit_cast(unsigned, b); }
;     __device__ __forceinline__ void operator()(ACC_T, const Unit& u, int wr, int wc, int fr, int fq) const {
;     ...
;             for (int ai = 0; ai < 2; ++ai)
; #pragma unroll
;                 for (int m = 0; m < 4; ++m) { bf16_t* rowp = P + (size_t)(row0 + ai * HALF + m * 16) * PW + col0;
; #pragma unroll
;                     for (int bj = 0; bj < 2; ++bj) { const f32x4 v0 = acc[ai][bj][m][0] * sc, v1 = acc[ai][bj][m][1] * sc;
;                         u32x4 w; w.x = cvt_pk_bf16(v0[0], v0[1]); w.y = cvt_pk_bf16(v0[2], v0[3]); w.z = cvt_pk_bf16(v1[0], v1[1]); w.w = cvt_pk_bf16(v1[2], v1[3]);
;                         *(u32x4*)(rowp + bj * HALF) = w;
;                         if (u.pn == 8 || u.pn == 9) {
;                             float q = (v0[0] * v0[0] + v0[1] * v0[1]) + (v0[2] * v0[2] + v0[3] * v0[3]) + (v1[0] * v1[0] + v1[1] * v1[1]) + (v1[2] * v1[2] + v1[3] * v1[3]);
;                             q += __shfl_xor(q, 16); q += __shfl_xor(q, 32);
;                             if (fq == 0) __hip_atomic_fetch_add(kn2 + (size_t)((u.pn - 8) * 4 + bj * 2 + (wc >> 1)) * T + (row0 + ai * HALF + m * 16), q, __ATOMIC_RELAXED, __HIP_MEMORY_SCOPE_AGENT); } } }
.LBB0_342:
	s_waitcnt lgkmcnt(0)
	v_mov_b32_e32 v58, v130
	v_mov_b32_e32 v59, v130
	v_pk_mul_f32 v[56:57], v[58:59], v[56:57]
	v_pk_mul_f32 v[54:55], v[130:131], v[54:55]
	v_pk_mul_f32 v[52:53], v[58:59], v[52:53]
	v_pk_mul_f32 v[50:51], v[130:131], v[50:51]
	v_cvt_pk_bf16_f32 v60, v54, v55
	v_cvt_pk_bf16_f32 v61, v56, v57
	v_cvt_pk_bf16_f32 v62, v50, v51
	v_cvt_pk_bf16_f32 v63, v52, v53
	s_and_b64 vcc, exec, s[40:41]
	global_store_dwordx4 v[66:67], v[60:63], off offset:256 sc1
	s_cbranch_vccnz .LBB0_346
	v_mul_f32_e32 v0, v55, v55
	v_fmac_f32_e32 v0, v54, v54
	v_mul_f32_e32 v54, v57, v57
	v_fmac_f32_e32 v54, v56, v56
	v_mul_f32_e32 v51, v51, v51
	v_add_f32_e32 v0, v0, v54
	v_fmac_f32_e32 v51, v50, v50
	v_mul_f32_e32 v50, v53, v53
	v_add_f32_e32 v0, v0, v51
	v_fmac_f32_e32 v50, v52, v52
	v_and_b32_e32 v51, 64, v230
	v_add_f32_e32 v0, v50, v0
	v_xor_b32_e32 v50, 16, v230
	v_add_u32_e32 v51, 64, v51
	v_cmp_lt_i32_e32 vcc, v50, v51
	s_nop 1
	v_cndmask_b32_e32 v50, v230, v50, vcc
	v_lshlrev_b32_e32 v50, 2, v50
	ds_bpermute_b32 v50, v50, v0
	s_waitcnt lgkmcnt(0)
	v_add_f32_e32 v0, v0, v50
	v_xor_b32_e32 v50, 32, v230
	v_cmp_lt_i32_e32 vcc, v50, v51
	s_nop 1
	v_cndmask_b32_e32 v50, v230, v50, vcc
	v_lshlrev_b32_e32 v50, 2, v50
	ds_bpermute_b32 v50, v50, v0
	s_and_saveexec_b64 s[0:1], s[36:37]
	s_cbranch_execz .LBB0_345
	s_lshl_b32 s3, s2, 16
	v_readlane_b32 s14, v252, 17
	s_add_u32 s14, s14, s3
	v_readlane_b32 s3, v252, 18
	v_ashrrev_i32_e32 v163, 31, v162
	s_addc_u32 s15, s3, 0
	v_lshl_add_u64 v[52:53], v[162:163], 2, s[14:15]
	s_waitcnt lgkmcnt(0)
	v_add_f32_e32 v0, v0, v50
	v_add_co_u32_e32 v50, vcc, 0x20000, v52
	s_nop 1
	v_addc_co_u32_e32 v51, vcc, 0, v53, vcc
	global_atomic_add_f32 v[50:51], v0, off

; __device__ __forceinline__ unsigned cvt_pk_bf16(float lo, float hi) { f32x2 v = {lo, hi}; bf16x2_t b = __builtin_convertvector(v, bf16x2_t); return __builtin_bit_cast(unsigned, b); }
;     __device__ __forceinline__ void operator()(ACC_T, const Unit& u, int wr, int wc, int fr, int fq) const {
;     ...
;             for (int ai = 0; ai < 2; ++ai)
; #pragma unroll
;                 for (int m = 0; m < 4; ++m) { bf16_t* rowp = P + (size_t)(row0 + ai * HALF + m * 16) * PW + col0;
; #pragma unroll
;                     for (int bj = 0; bj < 2; ++bj) { const f32x4 v0 = acc[ai][bj][m][0] * sc, v1 = acc[ai][bj][m][1] * sc;
;                         u32x4 w; w.x = cvt_pk_bf16(v0[0], v0[1]); w.y = cvt_pk_bf16(v0[2], v0[3]); w.z = cvt_pk_bf16(v1[0], v1[1]); w.w = cvt_pk_bf16(v1[2], v1[3]);
;                         *(u32x4*)(rowp + bj * HALF) = w;
;                         if (u.pn == 8 || u.pn == 9) {
;                             float q = (v0[0] * v0[0] + v0[1] * v0[1]) + (v0[2] * v0[2] + v0[3] * v0[3]) + (v1[0] * v1[0] + v1[1] * v1[1]) + (v1[2] * v1[2] + v1[3] * v1[3]);
;                             q += __shfl_xor(q, 16); q += __shfl_xor(q, 32);
;                             if (fq == 0) __hip_atomic_fetch_add(kn2 + (size_t)((u.pn - 8) * 4 + bj * 2 + (wc >> 1)) * T + (row0 + ai * HALF + m * 16), q, __ATOMIC_RELAXED, __HIP_MEMORY_SCOPE_AGENT); } } }
.LBB0_346:
	v_readlane_b32 s0, v251, 56
	v_readlane_b32 s1, v251, 57
	v_pk_mul_f32 v[48:49], v[58:59], v[48:49]
	v_pk_mul_f32 v[46:47], v[130:131], v[46:47]
	s_waitcnt lgkmcnt(0)
	v_mov_b64_e32 v[50:51], s[0:1]
	s_movk_i32 s0, 0x1c00
	v_mad_i64_i32 v[50:51], s[0:1], v160, s0, v[50:51]
	v_pk_mul_f32 v[44:45], v[58:59], v[44:45]
	v_pk_mul_f32 v[42:43], v[130:131], v[42:43]
	v_lshl_add_u64 v[50:51], v[132:133], 1, v[50:51]
	v_cvt_pk_bf16_f32 v52, v46, v47
	v_cvt_pk_bf16_f32 v53, v48, v49
	v_cvt_pk_bf16_f32 v54, v42, v43
	v_cvt_pk_bf16_f32 v55, v44, v45
	s_and_b64 vcc, exec, s[40:41]
	global_store_dwordx4 v[50:51], v[52:55], off sc1
	s_cbranch_vccnz .LBB0_350
	v_mul_f32_e32 v0, v47, v47
	v_fmac_f32_e32 v0, v46, v46
	v_mul_f32_e32 v46, v49, v49
	v_fmac_f32_e32 v46, v48, v48
	v_mul_f32_e32 v43, v43, v43
	v_add_f32_e32 v0, v0, v46
	v_fmac_f32_e32 v43, v42, v42
	v_mul_f32_e32 v42, v45, v45
	v_add_f32_e32 v0, v0, v43
	v_fmac_f32_e32 v42, v44, v44
	v_and_b32_e32 v43, 64, v230
	v_add_f32_e32 v0, v42, v0
	v_xor_b32_e32 v42, 16, v230
	v_add_u32_e32 v43, 64, v43
	v_cmp_lt_i32_e32 vcc, v42, v43
	s_nop 1
	v_cndmask_b32_e32 v42, v230, v42, vcc
	v_lshlrev_b32_e32 v42, 2, v42
	ds_bpermute_b32 v42, v42, v0
	s_waitcnt lgkmcnt(0)
	v_add_f32_e32 v0, v0, v42
	v_xor_b32_e32 v42, 32, v230
	v_cmp_lt_i32_e32 vcc, v42, v43
	s_nop 1
	v_cndmask_b32_e32 v42, v230, v42, vcc
	v_lshlrev_b32_e32 v42, 2, v42
	ds_bpermute_b32 v42, v42, v0
	s_and_saveexec_b64 s[0:1], s[36:37]
	s_cbranch_execz .LBB0_349
	s_lshl_b32 s3, s2, 16
	v_readlane_b32 s14, v252, 17
	s_add_u32 s14, s14, s3
	v_readlane_b32 s3, v252, 18
	s_addc_u32 s15, s3, 0
	v_lshl_add_u64 v[44:45], v[158:159], 2, s[14:15]
	s_waitcnt lgkmcnt(0)
	v_add_f32_e32 v0, v0, v42
	global_atomic_add_f32 v[44:45], v0, off offset:576

; __device__ __forceinline__ unsigned cvt_pk_bf16(float lo, float hi) { f32x2 v = {lo, hi}; bf16x2_t b = __builtin_convertvector(v, bf16x2_t); return __builtin_bit_cast(unsigned, b); }
;     __device__ __forceinline__ void operator()(ACC_T, const Unit& u, int wr, int wc, int fr, int fq) const {
;     ...
;             for (int ai = 0; ai < 2; ++ai)
; #pragma unroll
;                 for (int m = 0; m < 4; ++m) { bf16_t* rowp = P + (size_t)(row0 + ai * HALF + m * 16) * PW + col0;
; #pragma unroll
;                     for (int bj = 0; bj < 2; ++bj) { const f32x4 v0 = acc[ai][bj][m][0] * sc, v1 = acc[ai][bj][m][1] * sc;
;                         u32x4 w; w.x = cvt_pk_bf16(v0[0], v0[1]); w.y = cvt_pk_bf16(v0[2], v0[3]); w.z = cvt_pk_bf16(v1[0], v1[1]); w.w = cvt_pk_bf16(v1[2], v1[3]);
;                         *(u32x4*)(rowp + bj * HALF) = w;
;                         if (u.pn == 8 || u.pn == 9) {
;                             float q = (v0[0] * v0[0] + v0[1] * v0[1]) + (v0[2] * v0[2] + v0[3] * v0[3]) + (v1[0] * v1[0] + v1[1] * v1[1]) + (v1[2] * v1[2] + v1[3] * v1[3]);
;                             q += __shfl_xor(q, 16); q += __shfl_xor(q, 32);
;                             if (fq == 0) __hip_atomic_fetch_add(kn2 + (size_t)((u.pn - 8) * 4 + bj * 2 + (wc >> 1)) * T + (row0 + ai * HALF + m * 16), q, __ATOMIC_RELAXED, __HIP_MEMORY_SCOPE_AGENT); } } }
.LBB0_350:
	s_waitcnt lgkmcnt(0)
	v_mov_b32_e32 v42, v130
	v_mov_b32_e32 v43, v130
	v_pk_mul_f32 v[40:41], v[42:43], v[40:41]
	v_pk_mul_f32 v[38:39], v[130:131], v[38:39]
	v_pk_mul_f32 v[36:37], v[42:43], v[36:37]
	v_pk_mul_f32 v[34:35], v[130:131], v[34:35]
	v_cvt_pk_bf16_f32 v44, v38, v39
	v_cvt_pk_bf16_f32 v45, v40, v41
	v_cvt_pk_bf16_f32 v46, v34, v35
	v_cvt_pk_bf16_f32 v47, v36, v37
	s_and_b64 vcc, exec, s[40:41]
	global_store_dwordx4 v[50:51], v[44:47], off offset:256 sc1
	s_cbranch_vccnz .LBB0_354
	v_mul_f32_e32 v0, v39, v39
	v_fmac_f32_e32 v0, v38, v38
	v_mul_f32_e32 v38, v41, v41
	v_fmac_f32_e32 v38, v40, v40
	v_mul_f32_e32 v35, v35, v35
	v_add_f32_e32 v0, v0, v38
	v_fmac_f32_e32 v35, v34, v34
	v_mul_f32_e32 v34, v37, v37
	v_add_f32_e32 v0, v0, v35
	v_fmac_f32_e32 v34, v36, v36
	v_and_b32_e32 v35, 64, v230
	v_add_f32_e32 v0, v34, v0
	v_xor_b32_e32 v34, 16, v230
	v_add_u32_e32 v35, 64, v35
	v_cmp_lt_i32_e32 vcc, v34, v35
	s_nop 1
	v_cndmask_b32_e32 v34, v230, v34, vcc
	v_lshlrev_b32_e32 v34, 2, v34
	ds_bpermute_b32 v34, v34, v0
	s_waitcnt lgkmcnt(0)
	v_add_f32_e32 v0, v0, v34
	v_xor_b32_e32 v34, 32, v230
	v_cmp_lt_i32_e32 vcc, v34, v35
	s_nop 1
	v_cndmask_b32_e32 v34, v230, v34, vcc
	v_lshlrev_b32_e32 v34, 2, v34
	ds_bpermute_b32 v34, v34, v0
	s_and_saveexec_b64 s[0:1], s[36:37]
	s_cbranch_execz .LBB0_353
	s_lshl_b32 s3, s2, 16
	v_readlane_b32 s14, v252, 17
	s_add_u32 s14, s14, s3
	v_readlane_b32 s3, v252, 18
	v_ashrrev_i32_e32 v161, 31, v160
	s_addc_u32 s15, s3, 0
	v_lshl_add_u64 v[36:37], v[160:161], 2, s[14:15]
	s_waitcnt lgkmcnt(0)
	v_add_f32_e32 v0, v0, v34
	v_add_co_u32_e32 v34, vcc, 0x20000, v36
	s_nop 1
	v_addc_co_u32_e32 v35, vcc, 0, v37, vcc
	global_atomic_add_f32 v[34:35], v0, off

; __device__ __forceinline__ unsigned cvt_pk_bf16(float lo, float hi) { f32x2 v = {lo, hi}; bf16x2_t b = __builtin_convertvector(v, bf16x2_t); return __builtin_bit_cast(unsigned, b); }
;     __device__ __forceinline__ void operator()(ACC_T, const Unit& u, int wr, int wc, int fr, int fq) const {
;     ...
;             for (int ai = 0; ai < 2; ++ai)
; #pragma unroll
;                 for (int m = 0; m < 4; ++m) { bf16_t* rowp = P + (size_t)(row0 + ai * HALF + m * 16) * PW + col0;
; #pragma unroll
;                     for (int bj = 0; bj < 2; ++bj) { const f32x4 v0 = acc[ai][bj][m][0] * sc, v1 = acc[ai][bj][m][1] * sc;
;                         u32x4 w; w.x = cvt_pk_bf16(v0[0], v0[1]); w.y = cvt_pk_bf16(v0[2], v0[3]); w.z = cvt_pk_bf16(v1[0], v1[1]); w.w = cvt_pk_bf16(v1[2], v1[3]);
;                         *(u32x4*)(rowp + bj * HALF) = w;
;                         if (u.pn == 8 || u.pn == 9) {
;                             float q = (v0[0] * v0[0] + v0[1] * v0[1]) + (v0[2] * v0[2] + v0[3] * v0[3]) + (v1[0] * v1[0] + v1[1] * v1[1]) + (v1[2] * v1[2] + v1[3] * v1[3]);
;                             q += __shfl_xor(q, 16); q += __shfl_xor(q, 32);
;                             if (fq == 0) __hip_atomic_fetch_add(kn2 + (size_t)((u.pn - 8) * 4 + bj * 2 + (wc >> 1)) * T + (row0 + ai * HALF + m * 16), q, __ATOMIC_RELAXED, __HIP_MEMORY_SCOPE_AGENT); } } }
.LBB0_354:
	v_readlane_b32 s0, v251, 56
	v_readlane_b32 s1, v251, 57
	s_waitcnt lgkmcnt(0)
	v_add_u32_e32 v34, 0xa0, v158
	v_pk_mul_f32 v[32:33], v[42:43], v[32:33]
	v_mov_b64_e32 v[36:37], s[0:1]
	s_movk_i32 s0, 0x1c00
	v_mad_i64_i32 v[36:37], s[0:1], v34, s0, v[36:37]
	v_pk_mul_f32 v[30:31], v[130:131], v[30:31]
	v_pk_mul_f32 v[28:29], v[42:43], v[28:29]
	v_pk_mul_f32 v[26:27], v[130:131], v[26:27]
	v_lshl_add_u64 v[36:37], v[132:133], 1, v[36:37]
	v_cvt_pk_bf16_f32 v38, v30, v31
	v_cvt_pk_bf16_f32 v39, v32, v33
	v_cvt_pk_bf16_f32 v40, v26, v27
	v_cvt_pk_bf16_f32 v41, v28, v29
	s_and_b64 vcc, exec, s[40:41]
	global_store_dwordx4 v[36:37], v[38:41], off sc1
	s_cbranch_vccnz .LBB0_358
	v_mul_f32_e32 v0, v31, v31
	v_fmac_f32_e32 v0, v30, v30
	v_mul_f32_e32 v30, v33, v33
	v_fmac_f32_e32 v30, v32, v32
	v_mul_f32_e32 v27, v27, v27
	v_add_f32_e32 v0, v0, v30
	v_fmac_f32_e32 v27, v26, v26
	v_mul_f32_e32 v26, v29, v29
	v_add_f32_e32 v0, v0, v27
	v_fmac_f32_e32 v26, v28, v28
	v_and_b32_e32 v27, 64, v230
	v_add_f32_e32 v0, v26, v0
	v_xor_b32_e32 v26, 16, v230
	v_add_u32_e32 v27, 64, v27
	v_cmp_lt_i32_e32 vcc, v26, v27
	s_nop 1
	v_cndmask_b32_e32 v26, v230, v26, vcc
	v_lshlrev_b32_e32 v26, 2, v26
	ds_bpermute_b32 v26, v26, v0
	s_waitcnt lgkmcnt(0)
	v_add_f32_e32 v0, v0, v26
	v_xor_b32_e32 v26, 32, v230
	v_cmp_lt_i32_e32 vcc, v26, v27
	s_nop 1
	v_cndmask_b32_e32 v26, v230, v26, vcc
	v_lshlrev_b32_e32 v26, 2, v26
	ds_bpermute_b32 v26, v26, v0
	s_and_saveexec_b64 s[0:1], s[36:37]
	s_cbranch_execz .LBB0_357
	s_lshl_b32 s3, s2, 16
	v_readlane_b32 s14, v252, 17
	s_add_u32 s14, s14, s3
	v_readlane_b32 s3, v252, 18
	s_addc_u32 s15, s3, 0
	v_lshl_add_u64 v[28:29], v[158:159], 2, s[14:15]
	s_waitcnt lgkmcnt(0)
	v_add_f32_e32 v0, v0, v26
	global_atomic_add_f32 v[28:29], v0, off offset:640

; __device__ __forceinline__ unsigned cvt_pk_bf16(float lo, float hi) { f32x2 v = {lo, hi}; bf16x2_t b = __builtin_convertvector(v, bf16x2_t); return __builtin_bit_cast(unsigned, b); }
;     __device__ __forceinline__ void operator()(ACC_T, const Unit& u, int wr, int wc, int fr, int fq) const {
;     ...
;             for (int ai = 0; ai < 2; ++ai)
; #pragma unroll
;                 for (int m = 0; m < 4; ++m) { bf16_t* rowp = P + (size_t)(row0 + ai * HALF + m * 16) * PW + col0;
; #pragma unroll
;                     for (int bj = 0; bj < 2; ++bj) { const f32x4 v0 = acc[ai][bj][m][0] * sc, v1 = acc[ai][bj][m][1] * sc;
;                         u32x4 w; w.x = cvt_pk_bf16(v0[0], v0[1]); w.y = cvt_pk_bf16(v0[2], v0[3]); w.z = cvt_pk_bf16(v1[0], v1[1]); w.w = cvt_pk_bf16(v1[2], v1[3]);
;                         *(u32x4*)(rowp + bj * HALF) = w;
;                         if (u.pn == 8 || u.pn == 9) {
;                             float q = (v0[0] * v0[0] + v0[1] * v0[1]) + (v0[2] * v0[2] + v0[3] * v0[3]) + (v1[0] * v1[0] + v1[1] * v1[1]) + (v1[2] * v1[2] + v1[3] * v1[3]);
;                             q += __shfl_xor(q, 16); q += __shfl_xor(q, 32);
;                             if (fq == 0) __hip_atomic_fetch_add(kn2 + (size_t)((u.pn - 8) * 4 + bj * 2 + (wc >> 1)) * T + (row0 + ai * HALF + m * 16), q, __ATOMIC_RELAXED, __HIP_MEMORY_SCOPE_AGENT); } } }
.LBB0_358:
	s_waitcnt lgkmcnt(0)
	v_mov_b32_e32 v26, v130
	v_mov_b32_e32 v27, v130
	v_pk_mul_f32 v[24:25], v[26:27], v[24:25]
	v_pk_mul_f32 v[22:23], v[130:131], v[22:23]
	v_pk_mul_f32 v[20:21], v[26:27], v[20:21]
	v_pk_mul_f32 v[18:19], v[130:131], v[18:19]
	v_cvt_pk_bf16_f32 v28, v22, v23
	v_cvt_pk_bf16_f32 v29, v24, v25
	v_cvt_pk_bf16_f32 v30, v18, v19
	v_cvt_pk_bf16_f32 v31, v20, v21
	s_and_b64 vcc, exec, s[40:41]
	global_store_dwordx4 v[36:37], v[28:31], off offset:256 sc1
	s_cbranch_vccnz .LBB0_362
	v_mul_f32_e32 v0, v23, v23
	v_fmac_f32_e32 v0, v22, v22
	v_mul_f32_e32 v22, v25, v25
	v_fmac_f32_e32 v22, v24, v24
	v_mul_f32_e32 v19, v19, v19
	v_add_f32_e32 v0, v0, v22
	v_fmac_f32_e32 v19, v18, v18
	v_mul_f32_e32 v18, v21, v21
	v_add_f32_e32 v0, v0, v19
	v_fmac_f32_e32 v18, v20, v20
	v_and_b32_e32 v19, 64, v230
	v_add_f32_e32 v0, v18, v0
	v_xor_b32_e32 v18, 16, v230
	v_add_u32_e32 v19, 64, v19
	v_cmp_lt_i32_e32 vcc, v18, v19
	s_nop 1
	v_cndmask_b32_e32 v18, v230, v18, vcc
	v_lshlrev_b32_e32 v18, 2, v18
	ds_bpermute_b32 v18, v18, v0
	s_waitcnt lgkmcnt(0)
	v_add_f32_e32 v0, v0, v18
	v_xor_b32_e32 v18, 32, v230
	v_cmp_lt_i32_e32 vcc, v18, v19
	s_nop 1
	v_cndmask_b32_e32 v18, v230, v18, vcc
	v_lshlrev_b32_e32 v18, 2, v18
	ds_bpermute_b32 v18, v18, v0
	s_and_saveexec_b64 s[0:1], s[36:37]
	s_cbranch_execz .LBB0_361
	s_lshl_b32 s3, s2, 16
	v_readlane_b32 s14, v252, 17
	s_add_u32 s14, s14, s3
	v_readlane_b32 s3, v252, 18
	v_ashrrev_i32_e32 v35, 31, v34
	s_addc_u32 s15, s3, 0
	v_lshl_add_u64 v[20:21], v[34:35], 2, s[14:15]
	s_waitcnt lgkmcnt(0)
	v_add_f32_e32 v0, v0, v18
	v_add_co_u32_e32 v18, vcc, 0x20000, v20
	s_nop 1
	v_addc_co_u32_e32 v19, vcc, 0, v21, vcc
	global_atomic_add_f32 v[18:19], v0, off

; __device__ __forceinline__ unsigned cvt_pk_bf16(float lo, float hi) { f32x2 v = {lo, hi}; bf16x2_t b = __builtin_convertvector(v, bf16x2_t); return __builtin_bit_cast(unsigned, b); }
;     __device__ __forceinline__ void operator()(ACC_T, const Unit& u, int wr, int wc, int fr, int fq) const {
;     ...
;             for (int ai = 0; ai < 2; ++ai)
; #pragma unroll
;                 for (int m = 0; m < 4; ++m) { bf16_t* rowp = P + (size_t)(row0 + ai * HALF + m * 16) * PW + col0;
; #pragma unroll
;                     for (int bj = 0; bj < 2; ++bj) { const f32x4 v0 = acc[ai][bj][m][0] * sc, v1 = acc[ai][bj][m][1] * sc;
;                         u32x4 w; w.x = cvt_pk_bf16(v0[0], v0[1]); w.y = cvt_pk_bf16(v0[2], v0[3]); w.z = cvt_pk_bf16(v1[0], v1[1]); w.w = cvt_pk_bf16(v1[2], v1[3]);
;                         *(u32x4*)(rowp + bj * HALF) = w;
;                         if (u.pn == 8 || u.pn == 9) {
;                             float q = (v0[0] * v0[0] + v0[1] * v0[1]) + (v0[2] * v0[2] + v0[3] * v0[3]) + (v1[0] * v1[0] + v1[1] * v1[1]) + (v1[2] * v1[2] + v1[3] * v1[3]);
;                             q += __shfl_xor(q, 16); q += __shfl_xor(q, 32);
;                             if (fq == 0) __hip_atomic_fetch_add(kn2 + (size_t)((u.pn - 8) * 4 + bj * 2 + (wc >> 1)) * T + (row0 + ai * HALF + m * 16), q, __ATOMIC_RELAXED, __HIP_MEMORY_SCOPE_AGENT); } } }
.LBB0_362:
	v_readlane_b32 s0, v251, 56
	v_readlane_b32 s1, v251, 57
	s_waitcnt lgkmcnt(0)
	v_add_u32_e32 v18, 0xb0, v158
	v_pk_mul_f32 v[16:17], v[26:27], v[16:17]
	v_mov_b64_e32 v[20:21], s[0:1]
	s_movk_i32 s0, 0x1c00
	v_mad_i64_i32 v[20:21], s[0:1], v18, s0, v[20:21]
	v_pk_mul_f32 v[14:15], v[130:131], v[14:15]
	v_pk_mul_f32 v[12:13], v[26:27], v[12:13]
	v_pk_mul_f32 v[10:11], v[130:131], v[10:11]
	v_lshl_add_u64 v[20:21], v[132:133], 1, v[20:21]
	v_cvt_pk_bf16_f32 v22, v14, v15
	v_cvt_pk_bf16_f32 v23, v16, v17
	v_cvt_pk_bf16_f32 v24, v10, v11
	v_cvt_pk_bf16_f32 v25, v12, v13
	s_and_b64 vcc, exec, s[40:41]
	global_store_dwordx4 v[20:21], v[22:25], off sc1
	s_cbranch_vccnz .LBB0_366
	v_mul_f32_e32 v0, v15, v15
	v_fmac_f32_e32 v0, v14, v14
	v_mul_f32_e32 v14, v17, v17
	v_fmac_f32_e32 v14, v16, v16
	v_mul_f32_e32 v11, v11, v11
	v_add_f32_e32 v0, v0, v14
	v_fmac_f32_e32 v11, v10, v10
	v_mul_f32_e32 v10, v13, v13
	v_add_f32_e32 v0, v0, v11
	v_fmac_f32_e32 v10, v12, v12
	v_and_b32_e32 v11, 64, v230
	v_add_f32_e32 v0, v10, v0
	v_xor_b32_e32 v10, 16, v230
	v_add_u32_e32 v11, 64, v11
	v_cmp_lt_i32_e32 vcc, v10, v11
	s_nop 1
	v_cndmask_b32_e32 v10, v230, v10, vcc
	v_lshlrev_b32_e32 v10, 2, v10
	ds_bpermute_b32 v10, v10, v0
	s_waitcnt lgkmcnt(0)
	v_add_f32_e32 v0, v0, v10
	v_xor_b32_e32 v10, 32, v230
	v_cmp_lt_i32_e32 vcc, v10, v11
	s_nop 1
	v_cndmask_b32_e32 v10, v230, v10, vcc
	v_lshlrev_b32_e32 v10, 2, v10
	ds_bpermute_b32 v10, v10, v0
	s_and_saveexec_b64 s[0:1], s[36:37]
	s_cbranch_execz .LBB0_365
	s_lshl_b32 s3, s2, 16
	v_readlane_b32 s14, v252, 17
	s_add_u32 s14, s14, s3
	v_readlane_b32 s3, v252, 18
	s_addc_u32 s15, s3, 0
	v_lshl_add_u64 v[12:13], v[158:159], 2, s[14:15]
	s_waitcnt lgkmcnt(0)
	v_add_f32_e32 v0, v0, v10
	global_atomic_add_f32 v[12:13], v0, off offset:704

; __device__ __forceinline__ unsigned cvt_pk_bf16(float lo, float hi) { f32x2 v = {lo, hi}; bf16x2_t b = __builtin_convertvector(v, bf16x2_t); return __builtin_bit_cast(unsigned, b); }
;     __device__ __forceinline__ void operator()(ACC_T, const Unit& u, int wr, int wc, int fr, int fq) const {
;     ...
;             for (int ai = 0; ai < 2; ++ai)
; #pragma unroll
;                 for (int m = 0; m < 4; ++m) { bf16_t* rowp = P + (size_t)(row0 + ai * HALF + m * 16) * PW + col0;
; #pragma unroll
;                     for (int bj = 0; bj < 2; ++bj) { const f32x4 v0 = acc[ai][bj][m][0] * sc, v1 = acc[ai][bj][m][1] * sc;
;                         u32x4 w; w.x = cvt_pk_bf16(v0[0], v0[1]); w.y = cvt_pk_bf16(v0[2], v0[3]); w.z = cvt_pk_bf16(v1[0], v1[1]); w.w = cvt_pk_bf16(v1[2], v1[3]);
;                         *(u32x4*)(rowp + bj * HALF) = w;
;                         if (u.pn == 8 || u.pn == 9) {
;                             float q = (v0[0] * v0[0] + v0[1] * v0[1]) + (v0[2] * v0[2] + v0[3] * v0[3]) + (v1[0] * v1[0] + v1[1] * v1[1]) + (v1[2] * v1[2] + v1[3] * v1[3]);
;                             q += __shfl_xor(q, 16); q += __shfl_xor(q, 32);
;                             if (fq == 0) __hip_atomic_fetch_add(kn2 + (size_t)((u.pn - 8) * 4 + bj * 2 + (wc >> 1)) * T + (row0 + ai * HALF + m * 16), q, __ATOMIC_RELAXED, __HIP_MEMORY_SCOPE_AGENT); } } }
.LBB0_366:
	s_waitcnt lgkmcnt(0)
	v_mov_b32_e32 v10, v130
	v_mov_b32_e32 v11, v130
	v_pk_mul_f32 v[8:9], v[10:11], v[8:9]
	v_pk_mul_f32 v[6:7], v[130:131], v[6:7]
	v_pk_mul_f32 v[4:5], v[10:11], v[4:5]
	v_pk_mul_f32 v[2:3], v[130:131], v[2:3]
	v_cvt_pk_bf16_f32 v10, v6, v7
	v_cvt_pk_bf16_f32 v11, v8, v9
	v_cvt_pk_bf16_f32 v12, v2, v3
	v_cvt_pk_bf16_f32 v13, v4, v5
	s_and_b64 vcc, exec, s[40:41]
	global_store_dwordx4 v[20:21], v[10:13], off offset:256 sc1
	s_cbranch_vccnz .LBB0_370
	v_mul_f32_e32 v0, v7, v7
	v_fmac_f32_e32 v0, v6, v6
	v_mul_f32_e32 v6, v9, v9
	v_fmac_f32_e32 v6, v8, v8
	v_mul_f32_e32 v3, v3, v3
	v_add_f32_e32 v0, v0, v6
	v_fmac_f32_e32 v3, v2, v2
	v_mul_f32_e32 v2, v5, v5
	v_add_f32_e32 v0, v0, v3
	v_fmac_f32_e32 v2, v4, v4
	v_and_b32_e32 v3, 64, v230
	v_add_f32_e32 v0, v2, v0
	v_xor_b32_e32 v2, 16, v230
	v_add_u32_e32 v3, 64, v3
	v_cmp_lt_i32_e32 vcc, v2, v3
	s_nop 1
	v_cndmask_b32_e32 v2, v230, v2, vcc
	v_lshlrev_b32_e32 v2, 2, v2
	ds_bpermute_b32 v2, v2, v0
	s_waitcnt lgkmcnt(0)
	v_add_f32_e32 v0, v0, v2
	v_xor_b32_e32 v2, 32, v230
	v_cmp_lt_i32_e32 vcc, v2, v3
	s_nop 1
	v_cndmask_b32_e32 v2, v230, v2, vcc
	v_lshlrev_b32_e32 v2, 2, v2
	ds_bpermute_b32 v2, v2, v0
	s_and_saveexec_b64 s[0:1], s[36:37]
	s_cbranch_execz .LBB0_369
	s_lshl_b32 s2, s2, 16
	v_readlane_b32 s3, v252, 17
	s_add_u32 s2, s3, s2
	v_readlane_b32 s3, v252, 18
	v_ashrrev_i32_e32 v19, 31, v18
	s_addc_u32 s3, s3, 0
	v_lshl_add_u64 v[4:5], v[18:19], 2, s[2:3]
	s_waitcnt lgkmcnt(0)
	v_add_f32_e32 v0, v0, v2
	v_add_co_u32_e32 v2, vcc, 0x20000, v4
	s_nop 1
	v_addc_co_u32_e32 v3, vcc, 0, v5, vcc
	global_atomic_add_f32 v[2:3], v0, off
